# sample-stream pool-mix instance also uses the once-loaded weights and streamed LDS reads; two far branches go through mid-code trampolines
# baseline (speedup 1.0000x reference)
; __device__ __forceinline__ f32x4 unpk4(u32x2 p) { f32x4 r; r[0] = __uint_as_float(p.x << 16); r[1] = __uint_as_float(p.x & 0xffff0000u); r[2] = __uint_as_float(p.y << 16); r[3] = __uint_as_float(p.y & 0xffff0000u); return r; }
; __device__ __forceinline__ u32x4 pk8(f32x4 a, f32x4 b) { const u32x2 p = pk4(a), q = pk4(b); return (u32x4){p.x, p.y, q.x, q.y}; }
; template <int K>
; __device__ __forceinline__ void epilogue_p(const f32x4 (&acc)[2][2][4][2], const Unit& u, const EpiDesc& E, const Ctx& C, int wr, int wc, int fr, int fq) {
;     ...
;                 for (int bj = 0; bj < 2; ++bj) h[m2][bj] = *(const u32x4*)(C.XB + (size_t)(row0 + 128 * ai + 16 * (2 * mh + m2)) * DM + 256 * u.pn + 128 * bj + lc8);
; #pragma unroll
;             for (int m2 = 0; m2 < 2; ++m2) {
;                 const int m = 2 * mh + m2;
;                 const int row = row0 + 128 * ai + 16 * m;
;                 float* dst = C.PA + (size_t)row * DM;
;                 if (E.final_) {
;                     if (row < NPR) { const int b = row / TP, t = row - b * TP; if (t >= 16) dst = C.out + OFF_YP + ((size_t)b * 4096 + (t - 16)) * 1024; }
;                     else if (row < MR) dst = C.out + OFF_YS + (size_t)(row - NPR) * 1024;
;                 }
;                 float ss = 0.f;
; #pragma unroll
;                 for (int bj = 0; bj < 2; ++bj) {
;                     const int col = 256 * u.pn + 128 * bj + lc8;
;                     const f32x4 hv0 = unpk4((u32x2){h[m2][bj].x, h[m2][bj].y}) + acc[ai][bj][m][0] * E.alpha, hv1 = unpk4((u32x2){h[m2][bj].z, h[m2][bj].w}) + acc[ai][bj][m][1] * E.alpha;
;                     if (E.final_) { *(f32x4*)(dst + col) = hv0; *(f32x4*)(dst + col + 4) = hv1; }
;                     else {
;                         *(u32x4*)(C.XB + (size_t)row * DM + col) = pk8(hv0, hv1);
;                         ss += hv0[0] * hv0[0] + hv0[1] * hv0[1] + hv0[2] * hv0[2] + hv0[3] * hv0[3] + hv1[0] * hv1[0] + hv1[1] * hv1[1] + hv1[2] * hv1[2] + hv1[3] * hv1[3];
;                     }
;                 }
;                 if (!E.final_) {
;                     ss += __shfl_xor(ss, 16); ss += __shfl_xor(ss, 32);
;                     if (fq == 0) unsafeAtomicAdd(E.rss_out + row, ss);
.Lres_new:
	s_lshl_b32 s22, s87, 8
	s_add_i32 s22, s22, s74
	v_or_b32_e32 v132, s22, v172
	v_readlane_b32 s2, v254, 29
	v_readlane_b32 s3, v254, 30
	v_lshl_or_b32 v165, s86, 8, v175
	v_lshlrev_b32_e32 v0, 11, v132
	v_lshl_add_u32 v0, v165, 1, v0
	v_and_b32_e32 v165, 16, v233
	v_lshrrev_b32_e32 v133, 1, v165
	v_add_u32_e32 v165, v165, v133
	v_add_u32_e32 v0, v0, v165
	v_mov_b32_e32 v164, v0
	v_and_b32_e32 v165, 0x30, v233
	v_add_u32_e32 v132, v132, v165
	v_lshlrev_b32_e32 v132, 2, v132
	s_waitcnt lgkmcnt(0)
	global_load_dwordx4 v[144:147], v0, s[2:3]
	global_load_dwordx4 v[148:151], v0, s[2:3] offset:256
	v_add_u32_e32 v0, 0x8000, v0
	global_load_dwordx4 v[152:155], v0, s[2:3]
	global_load_dwordx4 v[156:159], v0, s[2:3] offset:256
	v_add_u32_e32 v0, 0x8000, v0
	s_waitcnt vmcnt(2)
	v_permlane16_swap_b32_e32 v144, v146
	v_permlane16_swap_b32_e32 v145, v147
	v_permlane16_swap_b32_e32 v148, v150
	v_permlane16_swap_b32_e32 v149, v151
	v_lshlrev_b32_e32 v178, 16, v144
	v_lshlrev_b32_e32 v179, 16, v145
	v_lshlrev_b32_e32 v180, 16, v146
	v_lshlrev_b32_e32 v181, 16, v147
	v_and_b32_e32 v144, 0xffff0000, v144
	v_and_b32_e32 v145, 0xffff0000, v145
	v_and_b32_e32 v146, 0xffff0000, v146
	v_and_b32_e32 v147, 0xffff0000, v147
	v_fma_f32 v122, v122, s10, v178
	v_fma_f32 v123, v123, s10, v144
	v_fma_f32 v124, v124, s10, v179
	v_fma_f32 v125, v125, s10, v145
	v_fma_f32 v126, v126, s10, v180
	v_fma_f32 v127, v127, s10, v146
	v_fma_f32 v128, v128, s10, v181
	v_fma_f32 v129, v129, s10, v147
	v_mul_f32_e32 v130, v122, v122
	v_mul_f32_e32 v131, v123, v123
	v_fmac_f32_e32 v130, v124, v124
	v_fmac_f32_e32 v131, v125, v125
	v_fmac_f32_e32 v130, v126, v126
	v_fmac_f32_e32 v131, v127, v127
	v_fmac_f32_e32 v130, v128, v128
	v_fmac_f32_e32 v131, v129, v129
	v_cvt_pk_bf16_f32 v144, v122, v123
	v_cvt_pk_bf16_f32 v145, v124, v125
	v_cvt_pk_bf16_f32 v146, v126, v127
	v_cvt_pk_bf16_f32 v147, v128, v129
	v_lshlrev_b32_e32 v178, 16, v148
	v_lshlrev_b32_e32 v179, 16, v149
	v_lshlrev_b32_e32 v180, 16, v150
	v_lshlrev_b32_e32 v181, 16, v151
	v_and_b32_e32 v148, 0xffff0000, v148
	v_and_b32_e32 v149, 0xffff0000, v149
	v_and_b32_e32 v150, 0xffff0000, v150
	v_and_b32_e32 v151, 0xffff0000, v151
	v_fma_f32 v114, v114, s10, v178
	v_fma_f32 v115, v115, s10, v148
	v_fma_f32 v116, v116, s10, v179
	v_fma_f32 v117, v117, s10, v149
	v_fma_f32 v118, v118, s10, v180
	v_fma_f32 v119, v119, s10, v150
	v_fma_f32 v120, v120, s10, v181
	v_fma_f32 v121, v121, s10, v151
	v_fmac_f32_e32 v130, v114, v114
	v_fmac_f32_e32 v131, v115, v115
	v_fmac_f32_e32 v130, v116, v116
	v_fmac_f32_e32 v131, v117, v117
	v_fmac_f32_e32 v130, v118, v118
	v_fmac_f32_e32 v131, v119, v119
	v_fmac_f32_e32 v130, v120, v120
	v_fmac_f32_e32 v131, v121, v121
	v_cvt_pk_bf16_f32 v148, v114, v115
	v_cvt_pk_bf16_f32 v149, v116, v117
	v_cvt_pk_bf16_f32 v150, v118, v119
	v_cvt_pk_bf16_f32 v151, v120, v121
	v_add_f32_e32 v168, v130, v131
	s_nop 0
	v_permlane16_swap_b32_e32 v144, v146
	v_permlane16_swap_b32_e32 v145, v147
	v_permlane16_swap_b32_e32 v148, v150
	v_permlane16_swap_b32_e32 v149, v151
	global_store_dwordx4 v164, v[144:147], s[2:3]
	global_store_dwordx4 v164, v[148:151], s[2:3] offset:256
	v_add_u32_e32 v164, 0x8000, v164
	global_load_dwordx4 v[160:163], v0, s[2:3]
	global_load_dwordx4 v[122:125], v0, s[2:3] offset:256
	v_add_u32_e32 v0, 0x8000, v0
	global_load_dwordx4 v[126:129], v0, s[2:3]
	global_load_dwordx4 v[114:117], v0, s[2:3] offset:256
	v_add_u32_e32 v0, 0x28000, v0
	s_waitcnt vmcnt(6)
	v_permlane16_swap_b32_e32 v152, v154
	v_permlane16_swap_b32_e32 v153, v155
	v_permlane16_swap_b32_e32 v156, v158
	v_permlane16_swap_b32_e32 v157, v159
	v_lshlrev_b32_e32 v178, 16, v152
	v_lshlrev_b32_e32 v179, 16, v153
	v_lshlrev_b32_e32 v180, 16, v154
	v_lshlrev_b32_e32 v181, 16, v155
	v_and_b32_e32 v152, 0xffff0000, v152
	v_and_b32_e32 v153, 0xffff0000, v153
	v_and_b32_e32 v154, 0xffff0000, v154
	v_and_b32_e32 v155, 0xffff0000, v155
	v_fma_f32 v106, v106, s10, v178
	v_fma_f32 v107, v107, s10, v152
	v_fma_f32 v108, v108, s10, v179
	v_fma_f32 v109, v109, s10, v153
	v_fma_f32 v110, v110, s10, v180
	v_fma_f32 v111, v111, s10, v154
	v_fma_f32 v112, v112, s10, v181
	v_fma_f32 v113, v113, s10, v155
	v_mul_f32_e32 v130, v106, v106
	v_mul_f32_e32 v131, v107, v107
	v_fmac_f32_e32 v130, v108, v108
	v_fmac_f32_e32 v131, v109, v109
	v_fmac_f32_e32 v130, v110, v110
	v_fmac_f32_e32 v131, v111, v111
	v_fmac_f32_e32 v130, v112, v112
	v_fmac_f32_e32 v131, v113, v113
	v_cvt_pk_bf16_f32 v152, v106, v107
	v_cvt_pk_bf16_f32 v153, v108, v109
	v_cvt_pk_bf16_f32 v154, v110, v111
	v_cvt_pk_bf16_f32 v155, v112, v113
	v_lshlrev_b32_e32 v178, 16, v156
	v_lshlrev_b32_e32 v179, 16, v157
	v_lshlrev_b32_e32 v180, 16, v158
	v_lshlrev_b32_e32 v181, 16, v159
	v_and_b32_e32 v156, 0xffff0000, v156
	v_and_b32_e32 v157, 0xffff0000, v157
	v_and_b32_e32 v158, 0xffff0000, v158
	v_and_b32_e32 v159, 0xffff0000, v159
	v_fma_f32 v98, v98, s10, v178
	v_fma_f32 v99, v99, s10, v156
	v_fma_f32 v100, v100, s10, v179
	v_fma_f32 v101, v101, s10, v157
	v_fma_f32 v102, v102, s10, v180
	v_fma_f32 v103, v103, s10, v158
	v_fma_f32 v104, v104, s10, v181
	v_fma_f32 v105, v105, s10, v159
	v_fmac_f32_e32 v130, v98, v98
	v_fmac_f32_e32 v131, v99, v99
	v_fmac_f32_e32 v130, v100, v100
	v_fmac_f32_e32 v131, v101, v101
	v_fmac_f32_e32 v130, v102, v102
	v_fmac_f32_e32 v131, v103, v103
	v_fmac_f32_e32 v130, v104, v104
	v_fmac_f32_e32 v131, v105, v105
	v_cvt_pk_bf16_f32 v156, v98, v99
	v_cvt_pk_bf16_f32 v157, v100, v101
	v_cvt_pk_bf16_f32 v158, v102, v103
	v_cvt_pk_bf16_f32 v159, v104, v105
	v_add_f32_e32 v169, v130, v131
	s_nop 0
	v_permlane16_swap_b32_e32 v152, v154
	v_permlane16_swap_b32_e32 v153, v155
	v_permlane16_swap_b32_e32 v156, v158
	v_permlane16_swap_b32_e32 v157, v159
	global_store_dwordx4 v164, v[152:155], s[2:3]
	global_store_dwordx4 v164, v[156:159], s[2:3] offset:256
	v_add_u32_e32 v164, 0x8000, v164
	global_load_dwordx4 v[118:121], v0, s[2:3]
	global_load_dwordx4 v[106:109], v0, s[2:3] offset:256
	v_add_u32_e32 v0, 0x8000, v0
	s_waitcnt vmcnt(6)
; __device__ __forceinline__ f32x4 unpk4(u32x2 p) { f32x4 r; r[0] = __uint_as_float(p.x << 16); r[1] = __uint_as_float(p.x & 0xffff0000u); r[2] = __uint_as_float(p.y << 16); r[3] = __uint_as_float(p.y & 0xffff0000u); return r; }
; __device__ __forceinline__ u32x4 pk8(f32x4 a, f32x4 b) { const u32x2 p = pk4(a), q = pk4(b); return (u32x4){p.x, p.y, q.x, q.y}; }
; template <int K>
; __device__ __forceinline__ void epilogue_p(const f32x4 (&acc)[2][2][4][2], const Unit& u, const EpiDesc& E, const Ctx& C, int wr, int wc, int fr, int fq) {
;     ...
;                 for (int bj = 0; bj < 2; ++bj) h[m2][bj] = *(const u32x4*)(C.XB + (size_t)(row0 + 128 * ai + 16 * (2 * mh + m2)) * DM + 256 * u.pn + 128 * bj + lc8);
; #pragma unroll
;             for (int m2 = 0; m2 < 2; ++m2) {
;                 const int m = 2 * mh + m2;
;                 const int row = row0 + 128 * ai + 16 * m;
;                 float* dst = C.PA + (size_t)row * DM;
;                 if (E.final_) {
;                     if (row < NPR) { const int b = row / TP, t = row - b * TP; if (t >= 16) dst = C.out + OFF_YP + ((size_t)b * 4096 + (t - 16)) * 1024; }
;                     else if (row < MR) dst = C.out + OFF_YS + (size_t)(row - NPR) * 1024;
;                 }
;                 float ss = 0.f;
; #pragma unroll
;                 for (int bj = 0; bj < 2; ++bj) {
;                     const int col = 256 * u.pn + 128 * bj + lc8;
;                     const f32x4 hv0 = unpk4((u32x2){h[m2][bj].x, h[m2][bj].y}) + acc[ai][bj][m][0] * E.alpha, hv1 = unpk4((u32x2){h[m2][bj].z, h[m2][bj].w}) + acc[ai][bj][m][1] * E.alpha;
;                     if (E.final_) { *(f32x4*)(dst + col) = hv0; *(f32x4*)(dst + col + 4) = hv1; }
;                     else {
;                         *(u32x4*)(C.XB + (size_t)row * DM + col) = pk8(hv0, hv1);
;                         ss += hv0[0] * hv0[0] + hv0[1] * hv0[1] + hv0[2] * hv0[2] + hv0[3] * hv0[3] + hv1[0] * hv1[0] + hv1[1] * hv1[1] + hv1[2] * hv1[2] + hv1[3] * hv1[3];
;                     }
;                 }
;                 if (!E.final_) {
;                     ss += __shfl_xor(ss, 16); ss += __shfl_xor(ss, 32);
;                     if (fq == 0) unsafeAtomicAdd(E.rss_out + row, ss);
	v_permlane16_swap_b32_e32 v160, v162
	v_permlane16_swap_b32_e32 v161, v163
	v_permlane16_swap_b32_e32 v122, v124
	v_permlane16_swap_b32_e32 v123, v125
	v_lshlrev_b32_e32 v178, 16, v160
	v_lshlrev_b32_e32 v179, 16, v161
	v_lshlrev_b32_e32 v180, 16, v162
	v_lshlrev_b32_e32 v181, 16, v163
	v_and_b32_e32 v160, 0xffff0000, v160
	v_and_b32_e32 v161, 0xffff0000, v161
	v_and_b32_e32 v162, 0xffff0000, v162
	v_and_b32_e32 v163, 0xffff0000, v163
	v_fma_f32 v90, v90, s10, v178
	v_fma_f32 v91, v91, s10, v160
	v_fma_f32 v92, v92, s10, v179
	v_fma_f32 v93, v93, s10, v161
	v_fma_f32 v94, v94, s10, v180
	v_fma_f32 v95, v95, s10, v162
	v_fma_f32 v96, v96, s10, v181
	v_fma_f32 v97, v97, s10, v163
	v_mul_f32_e32 v130, v90, v90
	v_mul_f32_e32 v131, v91, v91
	v_fmac_f32_e32 v130, v92, v92
	v_fmac_f32_e32 v131, v93, v93
	v_fmac_f32_e32 v130, v94, v94
	v_fmac_f32_e32 v131, v95, v95
	v_fmac_f32_e32 v130, v96, v96
	v_fmac_f32_e32 v131, v97, v97
	v_cvt_pk_bf16_f32 v160, v90, v91
	v_cvt_pk_bf16_f32 v161, v92, v93
	v_cvt_pk_bf16_f32 v162, v94, v95
	v_cvt_pk_bf16_f32 v163, v96, v97
	v_lshlrev_b32_e32 v178, 16, v122
	v_lshlrev_b32_e32 v179, 16, v123
	v_lshlrev_b32_e32 v180, 16, v124
	v_lshlrev_b32_e32 v181, 16, v125
	v_and_b32_e32 v122, 0xffff0000, v122
	v_and_b32_e32 v123, 0xffff0000, v123
	v_and_b32_e32 v124, 0xffff0000, v124
	v_and_b32_e32 v125, 0xffff0000, v125
	v_fma_f32 v82, v82, s10, v178
	v_fma_f32 v83, v83, s10, v122
	v_fma_f32 v84, v84, s10, v179
	v_fma_f32 v85, v85, s10, v123
	v_fma_f32 v86, v86, s10, v180
	v_fma_f32 v87, v87, s10, v124
	v_fma_f32 v88, v88, s10, v181
	v_fma_f32 v89, v89, s10, v125
	v_fmac_f32_e32 v130, v82, v82
	v_fmac_f32_e32 v131, v83, v83
	v_fmac_f32_e32 v130, v84, v84
	v_fmac_f32_e32 v131, v85, v85
	v_fmac_f32_e32 v130, v86, v86
	v_fmac_f32_e32 v131, v87, v87
	v_fmac_f32_e32 v130, v88, v88
	v_fmac_f32_e32 v131, v89, v89
	v_cvt_pk_bf16_f32 v122, v82, v83
	v_cvt_pk_bf16_f32 v123, v84, v85
	v_cvt_pk_bf16_f32 v124, v86, v87
	v_cvt_pk_bf16_f32 v125, v88, v89
	v_add_f32_e32 v170, v130, v131
	s_nop 0
	v_permlane16_swap_b32_e32 v160, v162
	v_permlane16_swap_b32_e32 v161, v163
	v_permlane16_swap_b32_e32 v122, v124
	v_permlane16_swap_b32_e32 v123, v125
	global_store_dwordx4 v164, v[160:163], s[2:3]
	global_store_dwordx4 v164, v[122:125], s[2:3] offset:256
	v_add_u32_e32 v164, 0x8000, v164
	global_load_dwordx4 v[110:113], v0, s[2:3]
	global_load_dwordx4 v[98:101], v0, s[2:3] offset:256
	v_add_u32_e32 v0, 0x8000, v0
	s_waitcnt vmcnt(8)
	v_permlane16_swap_b32_e32 v126, v128
	v_permlane16_swap_b32_e32 v127, v129
	v_permlane16_swap_b32_e32 v114, v116
	v_permlane16_swap_b32_e32 v115, v117
	v_lshlrev_b32_e32 v178, 16, v126
	v_lshlrev_b32_e32 v179, 16, v127
	v_lshlrev_b32_e32 v180, 16, v128
	v_lshlrev_b32_e32 v181, 16, v129
	v_and_b32_e32 v126, 0xffff0000, v126
	v_and_b32_e32 v127, 0xffff0000, v127
	v_and_b32_e32 v128, 0xffff0000, v128
	v_and_b32_e32 v129, 0xffff0000, v129
	v_fma_f32 v74, v74, s10, v178
	v_fma_f32 v75, v75, s10, v126
	v_fma_f32 v76, v76, s10, v179
	v_fma_f32 v77, v77, s10, v127
	v_fma_f32 v78, v78, s10, v180
	v_fma_f32 v79, v79, s10, v128
	v_fma_f32 v80, v80, s10, v181
	v_fma_f32 v81, v81, s10, v129
	v_mul_f32_e32 v130, v74, v74
	v_mul_f32_e32 v131, v75, v75
	v_fmac_f32_e32 v130, v76, v76
	v_fmac_f32_e32 v131, v77, v77
	v_fmac_f32_e32 v130, v78, v78
	v_fmac_f32_e32 v131, v79, v79
	v_fmac_f32_e32 v130, v80, v80
	v_fmac_f32_e32 v131, v81, v81
	v_cvt_pk_bf16_f32 v126, v74, v75
	v_cvt_pk_bf16_f32 v127, v76, v77
	v_cvt_pk_bf16_f32 v128, v78, v79
	v_cvt_pk_bf16_f32 v129, v80, v81
	v_lshlrev_b32_e32 v178, 16, v114
	v_lshlrev_b32_e32 v179, 16, v115
	v_lshlrev_b32_e32 v180, 16, v116
	v_lshlrev_b32_e32 v181, 16, v117
	v_and_b32_e32 v114, 0xffff0000, v114
	v_and_b32_e32 v115, 0xffff0000, v115
	v_and_b32_e32 v116, 0xffff0000, v116
	v_and_b32_e32 v117, 0xffff0000, v117
	v_fma_f32 v66, v66, s10, v178
	v_fma_f32 v67, v67, s10, v114
	v_fma_f32 v68, v68, s10, v179
	v_fma_f32 v69, v69, s10, v115
	v_fma_f32 v70, v70, s10, v180
	v_fma_f32 v71, v71, s10, v116
	v_fma_f32 v72, v72, s10, v181
	v_fma_f32 v73, v73, s10, v117
	v_fmac_f32_e32 v130, v66, v66
	v_fmac_f32_e32 v131, v67, v67
	v_fmac_f32_e32 v130, v68, v68
	v_fmac_f32_e32 v131, v69, v69
	v_fmac_f32_e32 v130, v70, v70
	v_fmac_f32_e32 v131, v71, v71
	v_fmac_f32_e32 v130, v72, v72
	v_fmac_f32_e32 v131, v73, v73
	v_cvt_pk_bf16_f32 v114, v66, v67
	v_cvt_pk_bf16_f32 v115, v68, v69
	v_cvt_pk_bf16_f32 v116, v70, v71
	v_cvt_pk_bf16_f32 v117, v72, v73
	v_add_f32_e32 v171, v130, v131
	s_nop 0
	v_permlane16_swap_b32_e32 v126, v128
	v_permlane16_swap_b32_e32 v127, v129
	v_permlane16_swap_b32_e32 v114, v116
	v_permlane16_swap_b32_e32 v115, v117
	global_store_dwordx4 v164, v[126:129], s[2:3]
	global_store_dwordx4 v164, v[114:117], s[2:3] offset:256
	v_add_u32_e32 v164, 0x28000, v164
	global_load_dwordx4 v[102:105], v0, s[2:3]
	global_load_dwordx4 v[90:93], v0, s[2:3] offset:256
	v_add_u32_e32 v0, 0x8000, v0
	s_nop 1
	v_permlane16_swap_b32_e32 v168, v169
	v_permlane16_swap_b32_e32 v170, v171
	v_add_f32_e32 v168, v168, v169
	v_add_f32_e32 v170, v170, v171
	s_nop 1
	v_permlane32_swap_b32_e32 v168, v170
	v_add_f32_e32 v168, v168, v170
	global_atomic_add_f32 v132, v168, s[4:5]
	s_waitcnt vmcnt(9)
; __device__ __forceinline__ f32x4 unpk4(u32x2 p) { f32x4 r; r[0] = __uint_as_float(p.x << 16); r[1] = __uint_as_float(p.x & 0xffff0000u); r[2] = __uint_as_float(p.y << 16); r[3] = __uint_as_float(p.y & 0xffff0000u); return r; }
; __device__ __forceinline__ u32x4 pk8(f32x4 a, f32x4 b) { const u32x2 p = pk4(a), q = pk4(b); return (u32x4){p.x, p.y, q.x, q.y}; }
; template <int K>
; __device__ __forceinline__ void epilogue_p(const f32x4 (&acc)[2][2][4][2], const Unit& u, const EpiDesc& E, const Ctx& C, int wr, int wc, int fr, int fq) {
;     ...
;                 for (int bj = 0; bj < 2; ++bj) h[m2][bj] = *(const u32x4*)(C.XB + (size_t)(row0 + 128 * ai + 16 * (2 * mh + m2)) * DM + 256 * u.pn + 128 * bj + lc8);
; #pragma unroll
;             for (int m2 = 0; m2 < 2; ++m2) {
;                 const int m = 2 * mh + m2;
;                 const int row = row0 + 128 * ai + 16 * m;
;                 float* dst = C.PA + (size_t)row * DM;
;                 if (E.final_) {
;                     if (row < NPR) { const int b = row / TP, t = row - b * TP; if (t >= 16) dst = C.out + OFF_YP + ((size_t)b * 4096 + (t - 16)) * 1024; }
;                     else if (row < MR) dst = C.out + OFF_YS + (size_t)(row - NPR) * 1024;
;                 }
;                 float ss = 0.f;
; #pragma unroll
;                 for (int bj = 0; bj < 2; ++bj) {
;                     const int col = 256 * u.pn + 128 * bj + lc8;
;                     const f32x4 hv0 = unpk4((u32x2){h[m2][bj].x, h[m2][bj].y}) + acc[ai][bj][m][0] * E.alpha, hv1 = unpk4((u32x2){h[m2][bj].z, h[m2][bj].w}) + acc[ai][bj][m][1] * E.alpha;
;                     if (E.final_) { *(f32x4*)(dst + col) = hv0; *(f32x4*)(dst + col + 4) = hv1; }
;                     else {
;                         *(u32x4*)(C.XB + (size_t)row * DM + col) = pk8(hv0, hv1);
;                         ss += hv0[0] * hv0[0] + hv0[1] * hv0[1] + hv0[2] * hv0[2] + hv0[3] * hv0[3] + hv1[0] * hv1[0] + hv1[1] * hv1[1] + hv1[2] * hv1[2] + hv1[3] * hv1[3];
;                     }
;                 }
;                 if (!E.final_) {
;                     ss += __shfl_xor(ss, 16); ss += __shfl_xor(ss, 32);
;                     if (fq == 0) unsafeAtomicAdd(E.rss_out + row, ss);
	v_permlane16_swap_b32_e32 v118, v120
	v_permlane16_swap_b32_e32 v119, v121
	v_permlane16_swap_b32_e32 v106, v108
	v_permlane16_swap_b32_e32 v107, v109
	v_lshlrev_b32_e32 v178, 16, v118
	v_lshlrev_b32_e32 v179, 16, v119
	v_lshlrev_b32_e32 v180, 16, v120
	v_lshlrev_b32_e32 v181, 16, v121
	v_and_b32_e32 v118, 0xffff0000, v118
	v_and_b32_e32 v119, 0xffff0000, v119
	v_and_b32_e32 v120, 0xffff0000, v120
	v_and_b32_e32 v121, 0xffff0000, v121
	v_fma_f32 v58, v58, s10, v178
	v_fma_f32 v59, v59, s10, v118
	v_fma_f32 v60, v60, s10, v179
	v_fma_f32 v61, v61, s10, v119
	v_fma_f32 v62, v62, s10, v180
	v_fma_f32 v63, v63, s10, v120
	v_fma_f32 v64, v64, s10, v181
	v_fma_f32 v65, v65, s10, v121
	v_mul_f32_e32 v130, v58, v58
	v_mul_f32_e32 v131, v59, v59
	v_fmac_f32_e32 v130, v60, v60
	v_fmac_f32_e32 v131, v61, v61
	v_fmac_f32_e32 v130, v62, v62
	v_fmac_f32_e32 v131, v63, v63
	v_fmac_f32_e32 v130, v64, v64
	v_fmac_f32_e32 v131, v65, v65
	v_cvt_pk_bf16_f32 v118, v58, v59
	v_cvt_pk_bf16_f32 v119, v60, v61
	v_cvt_pk_bf16_f32 v120, v62, v63
	v_cvt_pk_bf16_f32 v121, v64, v65
	v_lshlrev_b32_e32 v178, 16, v106
	v_lshlrev_b32_e32 v179, 16, v107
	v_lshlrev_b32_e32 v180, 16, v108
	v_lshlrev_b32_e32 v181, 16, v109
	v_and_b32_e32 v106, 0xffff0000, v106
	v_and_b32_e32 v107, 0xffff0000, v107
	v_and_b32_e32 v108, 0xffff0000, v108
	v_and_b32_e32 v109, 0xffff0000, v109
	v_fma_f32 v50, v50, s10, v178
	v_fma_f32 v51, v51, s10, v106
	v_fma_f32 v52, v52, s10, v179
	v_fma_f32 v53, v53, s10, v107
	v_fma_f32 v54, v54, s10, v180
	v_fma_f32 v55, v55, s10, v108
	v_fma_f32 v56, v56, s10, v181
	v_fma_f32 v57, v57, s10, v109
	v_fmac_f32_e32 v130, v50, v50
	v_fmac_f32_e32 v131, v51, v51
	v_fmac_f32_e32 v130, v52, v52
	v_fmac_f32_e32 v131, v53, v53
	v_fmac_f32_e32 v130, v54, v54
	v_fmac_f32_e32 v131, v55, v55
	v_fmac_f32_e32 v130, v56, v56
	v_fmac_f32_e32 v131, v57, v57
	v_cvt_pk_bf16_f32 v106, v50, v51
	v_cvt_pk_bf16_f32 v107, v52, v53
	v_cvt_pk_bf16_f32 v108, v54, v55
	v_cvt_pk_bf16_f32 v109, v56, v57
	v_add_f32_e32 v168, v130, v131
	s_nop 0
	v_permlane16_swap_b32_e32 v118, v120
	v_permlane16_swap_b32_e32 v119, v121
	v_permlane16_swap_b32_e32 v106, v108
	v_permlane16_swap_b32_e32 v107, v109
	global_store_dwordx4 v164, v[118:121], s[2:3]
	global_store_dwordx4 v164, v[106:109], s[2:3] offset:256
	v_add_u32_e32 v164, 0x8000, v164
	global_load_dwordx4 v[94:97], v0, s[2:3]
	global_load_dwordx4 v[82:85], v0, s[2:3] offset:256
	s_waitcnt vmcnt(9)
	v_permlane16_swap_b32_e32 v110, v112
	v_permlane16_swap_b32_e32 v111, v113
	v_permlane16_swap_b32_e32 v98, v100
	v_permlane16_swap_b32_e32 v99, v101
	v_lshlrev_b32_e32 v178, 16, v110
	v_lshlrev_b32_e32 v179, 16, v111
	v_lshlrev_b32_e32 v180, 16, v112
	v_lshlrev_b32_e32 v181, 16, v113
	v_and_b32_e32 v110, 0xffff0000, v110
	v_and_b32_e32 v111, 0xffff0000, v111
	v_and_b32_e32 v112, 0xffff0000, v112
	v_and_b32_e32 v113, 0xffff0000, v113
	v_fma_f32 v42, v42, s10, v178
	v_fma_f32 v43, v43, s10, v110
	v_fma_f32 v44, v44, s10, v179
	v_fma_f32 v45, v45, s10, v111
	v_fma_f32 v46, v46, s10, v180
	v_fma_f32 v47, v47, s10, v112
	v_fma_f32 v48, v48, s10, v181
	v_fma_f32 v49, v49, s10, v113
	v_mul_f32_e32 v130, v42, v42
	v_mul_f32_e32 v131, v43, v43
	v_fmac_f32_e32 v130, v44, v44
	v_fmac_f32_e32 v131, v45, v45
	v_fmac_f32_e32 v130, v46, v46
	v_fmac_f32_e32 v131, v47, v47
	v_fmac_f32_e32 v130, v48, v48
	v_fmac_f32_e32 v131, v49, v49
	v_cvt_pk_bf16_f32 v110, v42, v43
	v_cvt_pk_bf16_f32 v111, v44, v45
	v_cvt_pk_bf16_f32 v112, v46, v47
	v_cvt_pk_bf16_f32 v113, v48, v49
	v_lshlrev_b32_e32 v178, 16, v98
	v_lshlrev_b32_e32 v179, 16, v99
	v_lshlrev_b32_e32 v180, 16, v100
	v_lshlrev_b32_e32 v181, 16, v101
	v_and_b32_e32 v98, 0xffff0000, v98
	v_and_b32_e32 v99, 0xffff0000, v99
	v_and_b32_e32 v100, 0xffff0000, v100
	v_and_b32_e32 v101, 0xffff0000, v101
	v_fma_f32 v34, v34, s10, v178
	v_fma_f32 v35, v35, s10, v98
	v_fma_f32 v36, v36, s10, v179
	v_fma_f32 v37, v37, s10, v99
	v_fma_f32 v38, v38, s10, v180
	v_fma_f32 v39, v39, s10, v100
	v_fma_f32 v40, v40, s10, v181
	v_fma_f32 v41, v41, s10, v101
	v_fmac_f32_e32 v130, v34, v34
	v_fmac_f32_e32 v131, v35, v35
	v_fmac_f32_e32 v130, v36, v36
	v_fmac_f32_e32 v131, v37, v37
	v_fmac_f32_e32 v130, v38, v38
	v_fmac_f32_e32 v131, v39, v39
	v_fmac_f32_e32 v130, v40, v40
	v_fmac_f32_e32 v131, v41, v41
	v_cvt_pk_bf16_f32 v98, v34, v35
	v_cvt_pk_bf16_f32 v99, v36, v37
	v_cvt_pk_bf16_f32 v100, v38, v39
	v_cvt_pk_bf16_f32 v101, v40, v41
	v_add_f32_e32 v169, v130, v131
	s_nop 0
	v_permlane16_swap_b32_e32 v110, v112
	v_permlane16_swap_b32_e32 v111, v113
	v_permlane16_swap_b32_e32 v98, v100
	v_permlane16_swap_b32_e32 v99, v101
	global_store_dwordx4 v164, v[110:113], s[2:3]
	global_store_dwordx4 v164, v[98:101], s[2:3] offset:256
	v_add_u32_e32 v164, 0x8000, v164
	s_waitcnt vmcnt(7)
; __device__ __forceinline__ f32x4 unpk4(u32x2 p) { f32x4 r; r[0] = __uint_as_float(p.x << 16); r[1] = __uint_as_float(p.x & 0xffff0000u); r[2] = __uint_as_float(p.y << 16); r[3] = __uint_as_float(p.y & 0xffff0000u); return r; }
; __device__ __forceinline__ u32x4 pk8(f32x4 a, f32x4 b) { const u32x2 p = pk4(a), q = pk4(b); return (u32x4){p.x, p.y, q.x, q.y}; }
; template <int K>
; __device__ __forceinline__ void epilogue_p(const f32x4 (&acc)[2][2][4][2], const Unit& u, const EpiDesc& E, const Ctx& C, int wr, int wc, int fr, int fq) {
;     ...
;                 for (int bj = 0; bj < 2; ++bj) h[m2][bj] = *(const u32x4*)(C.XB + (size_t)(row0 + 128 * ai + 16 * (2 * mh + m2)) * DM + 256 * u.pn + 128 * bj + lc8);
; #pragma unroll
;             for (int m2 = 0; m2 < 2; ++m2) {
;                 const int m = 2 * mh + m2;
;                 const int row = row0 + 128 * ai + 16 * m;
;                 float* dst = C.PA + (size_t)row * DM;
;                 if (E.final_) {
;                     if (row < NPR) { const int b = row / TP, t = row - b * TP; if (t >= 16) dst = C.out + OFF_YP + ((size_t)b * 4096 + (t - 16)) * 1024; }
;                     else if (row < MR) dst = C.out + OFF_YS + (size_t)(row - NPR) * 1024;
;                 }
;                 float ss = 0.f;
; #pragma unroll
;                 for (int bj = 0; bj < 2; ++bj) {
;                     const int col = 256 * u.pn + 128 * bj + lc8;
;                     const f32x4 hv0 = unpk4((u32x2){h[m2][bj].x, h[m2][bj].y}) + acc[ai][bj][m][0] * E.alpha, hv1 = unpk4((u32x2){h[m2][bj].z, h[m2][bj].w}) + acc[ai][bj][m][1] * E.alpha;
;                     if (E.final_) { *(f32x4*)(dst + col) = hv0; *(f32x4*)(dst + col + 4) = hv1; }
;                     else {
;                         *(u32x4*)(C.XB + (size_t)row * DM + col) = pk8(hv0, hv1);
;                         ss += hv0[0] * hv0[0] + hv0[1] * hv0[1] + hv0[2] * hv0[2] + hv0[3] * hv0[3] + hv1[0] * hv1[0] + hv1[1] * hv1[1] + hv1[2] * hv1[2] + hv1[3] * hv1[3];
;                     }
;                 }
;                 if (!E.final_) {
;                     ss += __shfl_xor(ss, 16); ss += __shfl_xor(ss, 32);
;                     if (fq == 0) unsafeAtomicAdd(E.rss_out + row, ss);
	v_permlane16_swap_b32_e32 v102, v104
	v_permlane16_swap_b32_e32 v103, v105
	v_permlane16_swap_b32_e32 v90, v92
	v_permlane16_swap_b32_e32 v91, v93
	v_lshlrev_b32_e32 v178, 16, v102
	v_lshlrev_b32_e32 v179, 16, v103
	v_lshlrev_b32_e32 v180, 16, v104
	v_lshlrev_b32_e32 v181, 16, v105
	v_and_b32_e32 v102, 0xffff0000, v102
	v_and_b32_e32 v103, 0xffff0000, v103
	v_and_b32_e32 v104, 0xffff0000, v104
	v_and_b32_e32 v105, 0xffff0000, v105
	v_fma_f32 v26, v26, s10, v178
	v_fma_f32 v27, v27, s10, v102
	v_fma_f32 v28, v28, s10, v179
	v_fma_f32 v29, v29, s10, v103
	v_fma_f32 v30, v30, s10, v180
	v_fma_f32 v31, v31, s10, v104
	v_fma_f32 v32, v32, s10, v181
	v_fma_f32 v33, v33, s10, v105
	v_mul_f32_e32 v130, v26, v26
	v_mul_f32_e32 v131, v27, v27
	v_fmac_f32_e32 v130, v28, v28
	v_fmac_f32_e32 v131, v29, v29
	v_fmac_f32_e32 v130, v30, v30
	v_fmac_f32_e32 v131, v31, v31
	v_fmac_f32_e32 v130, v32, v32
	v_fmac_f32_e32 v131, v33, v33
	v_cvt_pk_bf16_f32 v102, v26, v27
	v_cvt_pk_bf16_f32 v103, v28, v29
	v_cvt_pk_bf16_f32 v104, v30, v31
	v_cvt_pk_bf16_f32 v105, v32, v33
	v_lshlrev_b32_e32 v178, 16, v90
	v_lshlrev_b32_e32 v179, 16, v91
	v_lshlrev_b32_e32 v180, 16, v92
	v_lshlrev_b32_e32 v181, 16, v93
	v_and_b32_e32 v90, 0xffff0000, v90
	v_and_b32_e32 v91, 0xffff0000, v91
	v_and_b32_e32 v92, 0xffff0000, v92
	v_and_b32_e32 v93, 0xffff0000, v93
	v_fma_f32 v18, v18, s10, v178
	v_fma_f32 v19, v19, s10, v90
	v_fma_f32 v20, v20, s10, v179
	v_fma_f32 v21, v21, s10, v91
	v_fma_f32 v22, v22, s10, v180
	v_fma_f32 v23, v23, s10, v92
	v_fma_f32 v24, v24, s10, v181
	v_fma_f32 v25, v25, s10, v93
	v_fmac_f32_e32 v130, v18, v18
	v_fmac_f32_e32 v131, v19, v19
	v_fmac_f32_e32 v130, v20, v20
	v_fmac_f32_e32 v131, v21, v21
	v_fmac_f32_e32 v130, v22, v22
	v_fmac_f32_e32 v131, v23, v23
	v_fmac_f32_e32 v130, v24, v24
	v_fmac_f32_e32 v131, v25, v25
	v_cvt_pk_bf16_f32 v90, v18, v19
	v_cvt_pk_bf16_f32 v91, v20, v21
	v_cvt_pk_bf16_f32 v92, v22, v23
	v_cvt_pk_bf16_f32 v93, v24, v25
	v_add_f32_e32 v170, v130, v131
	s_nop 0
	v_permlane16_swap_b32_e32 v102, v104
	v_permlane16_swap_b32_e32 v103, v105
	v_permlane16_swap_b32_e32 v90, v92
	v_permlane16_swap_b32_e32 v91, v93
	global_store_dwordx4 v164, v[102:105], s[2:3]
	global_store_dwordx4 v164, v[90:93], s[2:3] offset:256
	v_add_u32_e32 v164, 0x8000, v164
	s_waitcnt vmcnt(4)
	v_permlane16_swap_b32_e32 v94, v96
	v_permlane16_swap_b32_e32 v95, v97
	v_permlane16_swap_b32_e32 v82, v84
	v_permlane16_swap_b32_e32 v83, v85
	v_lshlrev_b32_e32 v178, 16, v94
	v_lshlrev_b32_e32 v179, 16, v95
	v_lshlrev_b32_e32 v180, 16, v96
	v_lshlrev_b32_e32 v181, 16, v97
	v_and_b32_e32 v94, 0xffff0000, v94
	v_and_b32_e32 v95, 0xffff0000, v95
	v_and_b32_e32 v96, 0xffff0000, v96
	v_and_b32_e32 v97, 0xffff0000, v97
	v_fma_f32 v10, v10, s10, v178
	v_fma_f32 v11, v11, s10, v94
	v_fma_f32 v12, v12, s10, v179
	v_fma_f32 v13, v13, s10, v95
	v_fma_f32 v14, v14, s10, v180
	v_fma_f32 v15, v15, s10, v96
	v_fma_f32 v16, v16, s10, v181
	v_fma_f32 v17, v17, s10, v97
	v_mul_f32_e32 v130, v10, v10
	v_mul_f32_e32 v131, v11, v11
	v_fmac_f32_e32 v130, v12, v12
	v_fmac_f32_e32 v131, v13, v13
	v_fmac_f32_e32 v130, v14, v14
	v_fmac_f32_e32 v131, v15, v15
	v_fmac_f32_e32 v130, v16, v16
	v_fmac_f32_e32 v131, v17, v17
	v_cvt_pk_bf16_f32 v94, v10, v11
	v_cvt_pk_bf16_f32 v95, v12, v13
	v_cvt_pk_bf16_f32 v96, v14, v15
	v_cvt_pk_bf16_f32 v97, v16, v17
	v_lshlrev_b32_e32 v178, 16, v82
	v_lshlrev_b32_e32 v179, 16, v83
	v_lshlrev_b32_e32 v180, 16, v84
	v_lshlrev_b32_e32 v181, 16, v85
	v_and_b32_e32 v82, 0xffff0000, v82
	v_and_b32_e32 v83, 0xffff0000, v83
	v_and_b32_e32 v84, 0xffff0000, v84
	v_and_b32_e32 v85, 0xffff0000, v85
	v_fma_f32 v6, v6, s10, v178
	v_fma_f32 v7, v7, s10, v82
	v_fma_f32 v8, v8, s10, v179
	v_fma_f32 v9, v9, s10, v83
	v_fma_f32 v2, v2, s10, v180
	v_fma_f32 v3, v3, s10, v84
	v_fma_f32 v4, v4, s10, v181
	v_fma_f32 v5, v5, s10, v85
	v_fmac_f32_e32 v130, v6, v6
	v_fmac_f32_e32 v131, v7, v7
	v_fmac_f32_e32 v130, v8, v8
	v_fmac_f32_e32 v131, v9, v9
	v_fmac_f32_e32 v130, v2, v2
	v_fmac_f32_e32 v131, v3, v3
	v_fmac_f32_e32 v130, v4, v4
	v_fmac_f32_e32 v131, v5, v5
	v_cvt_pk_bf16_f32 v82, v6, v7
	v_cvt_pk_bf16_f32 v83, v8, v9
	v_cvt_pk_bf16_f32 v84, v2, v3
	v_cvt_pk_bf16_f32 v85, v4, v5
	v_add_f32_e32 v171, v130, v131
	s_nop 0
	v_permlane16_swap_b32_e32 v94, v96
	v_permlane16_swap_b32_e32 v95, v97
	v_permlane16_swap_b32_e32 v82, v84
	v_permlane16_swap_b32_e32 v83, v85
	global_store_dwordx4 v164, v[94:97], s[2:3]
	global_store_dwordx4 v164, v[82:85], s[2:3] offset:256
	s_nop 1
	v_permlane16_swap_b32_e32 v168, v169
	v_permlane16_swap_b32_e32 v170, v171
	v_add_f32_e32 v168, v168, v169
	v_add_f32_e32 v170, v170, v171
	s_nop 1
	v_permlane32_swap_b32_e32 v168, v170
	v_add_f32_e32 v168, v168, v170
	global_atomic_add_f32 v132, v168, s[4:5] offset:512
	s_branch .LBB0_245
.Ltramp_827:
	s_branch .LBB0_827
.Ltramp_15:
	s_branch .LBB0_15
.LBB0_458:
	v_lshl_add_u64 v[148:149], v[146:147], 2, v[158:159]
	global_store_dwordx4 v[148:149], v[130:133], off offset:576
	s_cbranch_execnz .LBB0_453

; template <int MODE>
; __device__ __forceinline__ void poolconv_wave(const Ctx& C, int l, int ch, int g, int lane, float* PL) {
;     ...
;     float p[16], acc[16];
; #pragma unroll
;     for (int i = 0; i < 16; ++i) { const int pos = pos0 + t0 + i; p[i] = s[15 + i] / (float)min(pos + 1, wnd) - a[i]; acc[i] = 0.f; }
;     const float* wp = C.in[13] + ((size_t)l * 4 + g) * 4096 + lane;
; #pragma unroll
;     for (int i = 0; i < 16; ++i) PL[i * 64 + lane] = p[i];
;     asm volatile("s_waitcnt lgkmcnt(0)" ::: "memory");
.LBB0_685:
	s_nop 0
	v_div_scale_f32 v3, s[16:17], v131, v131, v102
	v_rcp_f32_e32 v7, v3
	v_div_scale_f32 v8, vcc, v102, v131, v102
	v_fma_f32 v9, -v3, v7, 1.0
	v_fmac_f32_e32 v7, v9, v7
	v_mul_f32_e32 v9, v8, v7
	v_fma_f32 v10, -v3, v9, v8
	v_fmac_f32_e32 v9, v10, v7
	v_fma_f32 v3, -v3, v9, v8
	v_div_scale_f32 v8, s[16:17], v131, v131, v103
	v_rcp_f32_e32 v10, v8
	v_div_fmas_f32 v3, v3, v7, v9
	v_div_fixup_f32 v3, v3, v131, v102
	v_sub_f32_e32 v2, v3, v2
	v_fma_f32 v3, -v8, v10, 1.0
	v_fmac_f32_e32 v10, v3, v10
	v_div_scale_f32 v3, vcc, v103, v131, v103
	v_mul_f32_e32 v7, v3, v10
	v_fma_f32 v9, -v8, v7, v3
	v_fmac_f32_e32 v7, v9, v10
	v_fma_f32 v3, -v8, v7, v3
	v_div_scale_f32 v8, s[16:17], v131, v131, v96
	v_rcp_f32_e32 v9, v8
	v_div_fmas_f32 v3, v3, v10, v7
	v_div_fixup_f32 v3, v3, v131, v103
	v_sub_f32_e32 v3, v3, v84
	v_fma_f32 v7, -v8, v9, 1.0
	v_fmac_f32_e32 v9, v7, v9
	v_div_scale_f32 v7, vcc, v96, v131, v96
	v_mul_f32_e32 v10, v7, v9
	v_fma_f32 v11, -v8, v10, v7
	v_fmac_f32_e32 v10, v11, v9
	v_fma_f32 v7, -v8, v10, v7
	v_div_scale_f32 v8, s[16:17], v131, v131, v97
	v_rcp_f32_e32 v11, v8
	v_div_fmas_f32 v7, v7, v9, v10
	v_div_fixup_f32 v7, v7, v131, v96
	v_sub_f32_e32 v7, v7, v80
	v_fma_f32 v9, -v8, v11, 1.0
	v_fmac_f32_e32 v11, v9, v11
	v_div_scale_f32 v9, vcc, v97, v131, v97
	v_mul_f32_e32 v10, v9, v11
	v_fma_f32 v12, -v8, v10, v9
	v_fmac_f32_e32 v10, v12, v11
	v_fma_f32 v8, -v8, v10, v9
	v_div_scale_f32 v9, s[16:17], v131, v131, v94
	v_rcp_f32_e32 v12, v9
	v_div_fmas_f32 v8, v8, v11, v10
	v_div_fixup_f32 v8, v8, v131, v97
	v_sub_f32_e32 v8, v8, v85
	v_fma_f32 v10, -v9, v12, 1.0
	v_fmac_f32_e32 v12, v10, v12
	v_div_scale_f32 v10, vcc, v94, v131, v94
	v_mul_f32_e32 v11, v10, v12
	v_fma_f32 v13, -v9, v11, v10
	v_fmac_f32_e32 v11, v13, v12
	v_fma_f32 v9, -v9, v11, v10
	v_div_scale_f32 v10, s[16:17], v131, v131, v95
	v_rcp_f32_e32 v13, v10
	v_div_fmas_f32 v9, v9, v12, v11
	v_div_fixup_f32 v9, v9, v131, v94
	v_sub_f32_e32 v9, v9, v78
	v_fma_f32 v11, -v10, v13, 1.0
	v_fmac_f32_e32 v13, v11, v13
	v_div_scale_f32 v11, vcc, v95, v131, v95
	v_mul_f32_e32 v12, v11, v13
	v_fma_f32 v14, -v10, v12, v11
	v_fmac_f32_e32 v12, v14, v13
	v_fma_f32 v10, -v10, v12, v11
	v_div_scale_f32 v11, s[16:17], v131, v131, v92
	v_rcp_f32_e32 v14, v11
	v_div_fmas_f32 v10, v10, v13, v12
	v_div_fixup_f32 v10, v10, v131, v95
	v_sub_f32_e32 v10, v10, v82
	v_fma_f32 v12, -v11, v14, 1.0
	v_fmac_f32_e32 v14, v12, v14
	v_div_scale_f32 v12, vcc, v92, v131, v92
	v_mul_f32_e32 v13, v12, v14
	v_fma_f32 v15, -v11, v13, v12
	v_fmac_f32_e32 v13, v15, v14
	v_fma_f32 v11, -v11, v13, v12
	v_div_scale_f32 v12, s[16:17], v131, v131, v93
	v_rcp_f32_e32 v15, v12
	v_div_fmas_f32 v11, v11, v14, v13
	v_div_fixup_f32 v11, v11, v131, v92
	v_sub_f32_e32 v11, v11, v76
	v_fma_f32 v13, -v12, v15, 1.0
	v_fmac_f32_e32 v15, v13, v15
	v_div_scale_f32 v13, vcc, v93, v131, v93
	v_mul_f32_e32 v14, v13, v15
	v_fma_f32 v16, -v12, v14, v13
	v_fmac_f32_e32 v14, v16, v15
	v_fma_f32 v12, -v12, v14, v13
	v_div_scale_f32 v13, s[16:17], v131, v131, v90
	v_rcp_f32_e32 v16, v13
	v_div_fmas_f32 v12, v12, v15, v14
	v_div_fixup_f32 v12, v12, v131, v93
	v_sub_f32_e32 v12, v12, v83
	v_fma_f32 v14, -v13, v16, 1.0
	v_fmac_f32_e32 v16, v14, v16
	v_div_scale_f32 v14, vcc, v90, v131, v90
	v_mul_f32_e32 v15, v14, v16
	v_fma_f32 v17, -v13, v15, v14
	v_fmac_f32_e32 v15, v17, v16
	v_fma_f32 v13, -v13, v15, v14
	v_div_scale_f32 v14, s[16:17], v131, v131, v91
	v_rcp_f32_e32 v17, v14
	v_div_fmas_f32 v13, v13, v16, v15
	v_div_fixup_f32 v13, v13, v131, v90
	v_sub_f32_e32 v13, v13, v74
	v_fma_f32 v15, -v14, v17, 1.0
	v_fmac_f32_e32 v17, v15, v17
	v_div_scale_f32 v15, vcc, v91, v131, v91
	v_mul_f32_e32 v16, v15, v17
	v_fma_f32 v18, -v14, v16, v15
	v_fmac_f32_e32 v16, v18, v17
	v_fma_f32 v14, -v14, v16, v15
	v_div_scale_f32 v15, s[16:17], v131, v131, v88
	v_rcp_f32_e32 v18, v15
	v_div_fmas_f32 v14, v14, v17, v16
	v_div_fixup_f32 v14, v14, v131, v91
	v_sub_f32_e32 v14, v14, v70
	v_fma_f32 v16, -v15, v18, 1.0
	v_fmac_f32_e32 v18, v16, v18
	v_div_scale_f32 v16, vcc, v88, v131, v88
	v_mul_f32_e32 v17, v16, v18
	v_fma_f32 v19, -v15, v17, v16
	v_fmac_f32_e32 v17, v19, v18
	v_fma_f32 v15, -v15, v17, v16
	v_div_scale_f32 v16, s[16:17], v131, v131, v89
	v_rcp_f32_e32 v19, v16
	v_div_fmas_f32 v15, v15, v18, v17
	v_div_fixup_f32 v15, v15, v131, v88
	v_sub_f32_e32 v15, v15, v72
	v_fma_f32 v17, -v16, v19, 1.0
	v_fmac_f32_e32 v19, v17, v19
	v_div_scale_f32 v17, vcc, v89, v131, v89
	v_mul_f32_e32 v18, v17, v19
	v_fma_f32 v20, -v16, v18, v17
	v_fmac_f32_e32 v18, v20, v19
	v_fma_f32 v16, -v16, v18, v17
	v_div_scale_f32 v17, s[16:17], v131, v131, v86
	v_rcp_f32_e32 v20, v17
	v_div_fmas_f32 v16, v16, v19, v18
	v_div_fixup_f32 v16, v16, v131, v89
	v_sub_f32_e32 v16, v16, v71
	v_fma_f32 v18, -v17, v20, 1.0
	v_fmac_f32_e32 v20, v18, v20
	v_div_scale_f32 v18, vcc, v86, v131, v86
	v_mul_f32_e32 v19, v18, v20
	v_fma_f32 v21, -v17, v19, v18
	v_fmac_f32_e32 v19, v21, v20
	v_fma_f32 v17, -v17, v19, v18
	v_div_scale_f32 v18, s[16:17], v131, v131, v87
	v_rcp_f32_e32 v21, v18
	v_div_fmas_f32 v17, v17, v20, v19
	v_div_fixup_f32 v17, v17, v131, v86
	v_sub_f32_e32 v17, v17, v0
	v_fma_f32 v19, -v18, v21, 1.0
	v_fmac_f32_e32 v21, v19, v21
	v_div_scale_f32 v19, vcc, v87, v131, v87
	v_mul_f32_e32 v20, v19, v21
	v_fma_f32 v22, -v18, v20, v19
	v_fmac_f32_e32 v20, v22, v21
	v_fma_f32 v18, -v18, v20, v19
	v_div_scale_f32 v19, s[16:17], v131, v131, v4
	v_rcp_f32_e32 v22, v19
	v_div_fmas_f32 v18, v18, v21, v20
	v_div_fixup_f32 v18, v18, v131, v87
	v_sub_f32_e32 v18, v18, v6
	v_fma_f32 v20, -v19, v22, 1.0
	v_fmac_f32_e32 v22, v20, v22
	v_div_scale_f32 v20, vcc, v4, v131, v4
	v_mul_f32_e32 v21, v20, v22
	v_fma_f32 v23, -v19, v21, v20
	v_fmac_f32_e32 v21, v23, v22
	v_fma_f32 v19, -v19, v21, v20
	v_div_scale_f32 v20, s[16:17], v131, v131, v5
	v_rcp_f32_e32 v23, v20
	v_div_fmas_f32 v19, v19, v22, v21
	v_div_fixup_f32 v4, v19, v131, v4
	v_sub_f32_e32 v4, v4, v68
	v_fma_f32 v19, -v20, v23, 1.0
	v_fmac_f32_e32 v23, v19, v23
	v_div_scale_f32 v19, vcc, v5, v131, v5
	v_mul_f32_e32 v21, v19, v23
	v_fma_f32 v22, -v20, v21, v19
	v_fmac_f32_e32 v21, v22, v23
	v_fma_f32 v19, -v20, v21, v19
	v_div_fmas_f32 v19, v19, v23, v21
	v_div_fixup_f32 v5, v19, v131, v5
	v_sub_f32_e32 v5, v5, v69
	ds_write2st64_b32 v117, v2, v3 offset1:1
	ds_write2st64_b32 v117, v7, v8 offset0:2 offset1:3
	ds_write2st64_b32 v117, v9, v10 offset0:4 offset1:5
	ds_write2st64_b32 v117, v11, v12 offset0:6 offset1:7
	ds_write2st64_b32 v117, v13, v14 offset0:8 offset1:9
	ds_write2st64_b32 v117, v15, v16 offset0:10 offset1:11
	ds_write2st64_b32 v117, v17, v18 offset0:12 offset1:13
	ds_write2st64_b32 v117, v4, v5 offset0:14 offset1:15
	s_waitcnt lgkmcnt(0)
; template <int MODE>
; __device__ __forceinline__ void poolconv_wave(const Ctx& C, int l, int ch, int g, int lane, float* PL) {
;     ...
;     for (int i = 0; i < 16; ++i) PL[i * 64 + lane] = p[i];
;     asm volatile("s_waitcnt lgkmcnt(0)" ::: "memory");
; #pragma unroll 2
;     for (int k4 = 0; k4 < 16; ++k4) {
;         const float w0 = wp[(4 * k4 + 0) * 64], w1 = wp[(4 * k4 + 1) * 64], w2 = wp[(4 * k4 + 2) * 64], w3 = wp[(4 * k4 + 3) * 64];
; #pragma unroll
;         for (int i = 0; i < 16; ++i) { const f32x4 pv = *(const f32x4*)(PL + i * 64 + 4 * k4); acc[i] += pv[0] * w0 + pv[1] * w1 + pv[2] * w2 + pv[3] * w3; }
	s_waitcnt vmcnt(0)
	v_mov_b32_e32 v7, v116
	ds_read_b128 v[2:5], v7
	ds_read_b128 v[24:27], v7 offset:16
	ds_read_b128 v[28:31], v7 offset:32
	s_waitcnt lgkmcnt(2)
	v_mul_f32_e32 v8, v2, v146
	v_mul_f32_e32 v96, v3, v147
	v_fmac_f32_e32 v8, v4, v148
	v_fmac_f32_e32 v96, v5, v149
	ds_read_b128 v[2:5], v7 offset:48
	s_waitcnt lgkmcnt(2)
	v_fmac_f32_e32 v8, v24, v150
	v_fmac_f32_e32 v96, v25, v151
	v_fmac_f32_e32 v8, v26, v152
	v_fmac_f32_e32 v96, v27, v153
	ds_read_b128 v[24:27], v7 offset:64
	s_waitcnt lgkmcnt(2)
	v_fmac_f32_e32 v8, v28, v154
	v_fmac_f32_e32 v96, v29, v155
	v_fmac_f32_e32 v8, v30, v156
	v_fmac_f32_e32 v96, v31, v157
	ds_read_b128 v[28:31], v7 offset:80
	s_waitcnt lgkmcnt(2)
	v_fmac_f32_e32 v8, v2, v158
	v_fmac_f32_e32 v96, v3, v159
	v_fmac_f32_e32 v8, v4, v160
	v_fmac_f32_e32 v96, v5, v161
	ds_read_b128 v[2:5], v7 offset:96
	s_waitcnt lgkmcnt(2)
	v_fmac_f32_e32 v8, v24, v162
	v_fmac_f32_e32 v96, v25, v163
	v_fmac_f32_e32 v8, v26, v164
	v_fmac_f32_e32 v96, v27, v165
	ds_read_b128 v[24:27], v7 offset:112
	s_waitcnt lgkmcnt(2)
	v_fmac_f32_e32 v8, v28, v184
	v_fmac_f32_e32 v96, v29, v185
	v_fmac_f32_e32 v8, v30, v186
	v_fmac_f32_e32 v96, v31, v187
	ds_read_b128 v[28:31], v7 offset:128
	s_waitcnt lgkmcnt(2)
	v_fmac_f32_e32 v8, v2, v188
	v_fmac_f32_e32 v96, v3, v189
	v_fmac_f32_e32 v8, v4, v190
	v_fmac_f32_e32 v96, v5, v191
	ds_read_b128 v[2:5], v7 offset:144
	s_waitcnt lgkmcnt(2)
	v_fmac_f32_e32 v8, v24, v192
	v_fmac_f32_e32 v96, v25, v193
	v_fmac_f32_e32 v8, v26, v196
	v_fmac_f32_e32 v96, v27, v197
	ds_read_b128 v[24:27], v7 offset:160
	s_waitcnt lgkmcnt(2)
	v_fmac_f32_e32 v8, v28, v198
	v_fmac_f32_e32 v96, v29, v199
	v_fmac_f32_e32 v8, v30, v200
	v_fmac_f32_e32 v96, v31, v201
	ds_read_b128 v[28:31], v7 offset:176
	s_waitcnt lgkmcnt(2)
	v_fmac_f32_e32 v8, v2, v202
	v_fmac_f32_e32 v96, v3, v203
	v_fmac_f32_e32 v8, v4, v204
	v_fmac_f32_e32 v96, v5, v205
	ds_read_b128 v[2:5], v7 offset:192
	s_waitcnt lgkmcnt(2)
	v_fmac_f32_e32 v8, v24, v206
	v_fmac_f32_e32 v96, v25, v207
	v_fmac_f32_e32 v8, v26, v208
	v_fmac_f32_e32 v96, v27, v209
	ds_read_b128 v[24:27], v7 offset:208
	s_waitcnt lgkmcnt(2)
	v_fmac_f32_e32 v8, v28, v210
	v_fmac_f32_e32 v96, v29, v211
	v_fmac_f32_e32 v8, v30, v212
	v_fmac_f32_e32 v96, v31, v213
	ds_read_b128 v[28:31], v7 offset:224
	s_waitcnt lgkmcnt(2)
	v_fmac_f32_e32 v8, v2, v214
	v_fmac_f32_e32 v96, v3, v215
	v_fmac_f32_e32 v8, v4, v216
	v_fmac_f32_e32 v96, v5, v217
	ds_read_b128 v[2:5], v7 offset:240
	s_waitcnt lgkmcnt(2)
	v_fmac_f32_e32 v8, v24, v218
	v_fmac_f32_e32 v96, v25, v219
	v_fmac_f32_e32 v8, v26, v220
	v_fmac_f32_e32 v96, v27, v221
	ds_read_b128 v[24:27], v7 offset:256
	s_waitcnt lgkmcnt(2)
	v_fmac_f32_e32 v8, v28, v222
	v_fmac_f32_e32 v96, v29, v223
	v_fmac_f32_e32 v8, v30, v224
	v_fmac_f32_e32 v96, v31, v225
	ds_read_b128 v[28:31], v7 offset:272
	s_waitcnt lgkmcnt(2)
	v_fmac_f32_e32 v8, v2, v226
	v_fmac_f32_e32 v96, v3, v227
	v_fmac_f32_e32 v8, v4, v228
	v_fmac_f32_e32 v96, v5, v229
	v_add_f32_e32 v8, v8, v96
	ds_read_b128 v[2:5], v7 offset:288
	s_waitcnt lgkmcnt(2)
	v_mul_f32_e32 v9, v24, v146
	v_mul_f32_e32 v97, v25, v147
	v_fmac_f32_e32 v9, v26, v148
	v_fmac_f32_e32 v97, v27, v149
	ds_read_b128 v[24:27], v7 offset:304
	s_waitcnt lgkmcnt(2)
	v_fmac_f32_e32 v9, v28, v150
	v_fmac_f32_e32 v97, v29, v151
	v_fmac_f32_e32 v9, v30, v152
	v_fmac_f32_e32 v97, v31, v153
	ds_read_b128 v[28:31], v7 offset:320
	s_waitcnt lgkmcnt(2)
	v_fmac_f32_e32 v9, v2, v154
	v_fmac_f32_e32 v97, v3, v155
	v_fmac_f32_e32 v9, v4, v156
	v_fmac_f32_e32 v97, v5, v157
	ds_read_b128 v[2:5], v7 offset:336
	s_waitcnt lgkmcnt(2)
	v_fmac_f32_e32 v9, v24, v158
	v_fmac_f32_e32 v97, v25, v159
	v_fmac_f32_e32 v9, v26, v160
	v_fmac_f32_e32 v97, v27, v161
	ds_read_b128 v[24:27], v7 offset:352
	s_waitcnt lgkmcnt(2)
	v_fmac_f32_e32 v9, v28, v162
	v_fmac_f32_e32 v97, v29, v163
	v_fmac_f32_e32 v9, v30, v164
	v_fmac_f32_e32 v97, v31, v165
	ds_read_b128 v[28:31], v7 offset:368
	s_waitcnt lgkmcnt(2)
	v_fmac_f32_e32 v9, v2, v184
	v_fmac_f32_e32 v97, v3, v185
	v_fmac_f32_e32 v9, v4, v186
	v_fmac_f32_e32 v97, v5, v187
	ds_read_b128 v[2:5], v7 offset:384
	s_waitcnt lgkmcnt(2)
	v_fmac_f32_e32 v9, v24, v188
	v_fmac_f32_e32 v97, v25, v189
	v_fmac_f32_e32 v9, v26, v190
	v_fmac_f32_e32 v97, v27, v191
	ds_read_b128 v[24:27], v7 offset:400
	s_waitcnt lgkmcnt(2)
	v_fmac_f32_e32 v9, v28, v192
	v_fmac_f32_e32 v97, v29, v193
	v_fmac_f32_e32 v9, v30, v196
	v_fmac_f32_e32 v97, v31, v197
	ds_read_b128 v[28:31], v7 offset:416
	s_waitcnt lgkmcnt(2)
	v_fmac_f32_e32 v9, v2, v198
	v_fmac_f32_e32 v97, v3, v199
	v_fmac_f32_e32 v9, v4, v200
	v_fmac_f32_e32 v97, v5, v201
	ds_read_b128 v[2:5], v7 offset:432
	s_waitcnt lgkmcnt(2)
	v_fmac_f32_e32 v9, v24, v202
	v_fmac_f32_e32 v97, v25, v203
	v_fmac_f32_e32 v9, v26, v204
	v_fmac_f32_e32 v97, v27, v205
	ds_read_b128 v[24:27], v7 offset:448
	s_waitcnt lgkmcnt(2)
	v_fmac_f32_e32 v9, v28, v206
	v_fmac_f32_e32 v97, v29, v207
	v_fmac_f32_e32 v9, v30, v208
	v_fmac_f32_e32 v97, v31, v209
	ds_read_b128 v[28:31], v7 offset:464
	s_waitcnt lgkmcnt(2)
	v_fmac_f32_e32 v9, v2, v210
	v_fmac_f32_e32 v97, v3, v211
	v_fmac_f32_e32 v9, v4, v212
	v_fmac_f32_e32 v97, v5, v213
	ds_read_b128 v[2:5], v7 offset:480
	s_waitcnt lgkmcnt(2)
	v_fmac_f32_e32 v9, v24, v214
	v_fmac_f32_e32 v97, v25, v215
	v_fmac_f32_e32 v9, v26, v216
	v_fmac_f32_e32 v97, v27, v217
	ds_read_b128 v[24:27], v7 offset:496
	s_waitcnt lgkmcnt(2)
	v_fmac_f32_e32 v9, v28, v218
	v_fmac_f32_e32 v97, v29, v219
	v_fmac_f32_e32 v9, v30, v220
	v_fmac_f32_e32 v97, v31, v221
	ds_read_b128 v[28:31], v7 offset:512
	s_waitcnt lgkmcnt(2)
; template <int MODE>
; __device__ __forceinline__ void poolconv_wave(const Ctx& C, int l, int ch, int g, int lane, float* PL) {
;     ...
; #pragma unroll 2
;     for (int k4 = 0; k4 < 16; ++k4) {
;         const float w0 = wp[(4 * k4 + 0) * 64], w1 = wp[(4 * k4 + 1) * 64], w2 = wp[(4 * k4 + 2) * 64], w3 = wp[(4 * k4 + 3) * 64];
; #pragma unroll
;         for (int i = 0; i < 16; ++i) { const f32x4 pv = *(const f32x4*)(PL + i * 64 + 4 * k4); acc[i] += pv[0] * w0 + pv[1] * w1 + pv[2] * w2 + pv[3] * w3; }
;     }
	v_fmac_f32_e32 v9, v2, v222
	v_fmac_f32_e32 v97, v3, v223
	v_fmac_f32_e32 v9, v4, v224
	v_fmac_f32_e32 v97, v5, v225
	ds_read_b128 v[2:5], v7 offset:528
	s_waitcnt lgkmcnt(2)
	v_fmac_f32_e32 v9, v24, v226
	v_fmac_f32_e32 v97, v25, v227
	v_fmac_f32_e32 v9, v26, v228
	v_fmac_f32_e32 v97, v27, v229
	v_add_f32_e32 v9, v9, v97
	ds_read_b128 v[24:27], v7 offset:544
	s_waitcnt lgkmcnt(2)
	v_mul_f32_e32 v10, v28, v146
	v_mul_f32_e32 v96, v29, v147
	v_fmac_f32_e32 v10, v30, v148
	v_fmac_f32_e32 v96, v31, v149
	ds_read_b128 v[28:31], v7 offset:560
	s_waitcnt lgkmcnt(2)
	v_fmac_f32_e32 v10, v2, v150
	v_fmac_f32_e32 v96, v3, v151
	v_fmac_f32_e32 v10, v4, v152
	v_fmac_f32_e32 v96, v5, v153
	ds_read_b128 v[2:5], v7 offset:576
	s_waitcnt lgkmcnt(2)
	v_fmac_f32_e32 v10, v24, v154
	v_fmac_f32_e32 v96, v25, v155
	v_fmac_f32_e32 v10, v26, v156
	v_fmac_f32_e32 v96, v27, v157
	ds_read_b128 v[24:27], v7 offset:592
	s_waitcnt lgkmcnt(2)
	v_fmac_f32_e32 v10, v28, v158
	v_fmac_f32_e32 v96, v29, v159
	v_fmac_f32_e32 v10, v30, v160
	v_fmac_f32_e32 v96, v31, v161
	ds_read_b128 v[28:31], v7 offset:608
	s_waitcnt lgkmcnt(2)
	v_fmac_f32_e32 v10, v2, v162
	v_fmac_f32_e32 v96, v3, v163
	v_fmac_f32_e32 v10, v4, v164
	v_fmac_f32_e32 v96, v5, v165
	ds_read_b128 v[2:5], v7 offset:624
	s_waitcnt lgkmcnt(2)
	v_fmac_f32_e32 v10, v24, v184
	v_fmac_f32_e32 v96, v25, v185
	v_fmac_f32_e32 v10, v26, v186
	v_fmac_f32_e32 v96, v27, v187
	ds_read_b128 v[24:27], v7 offset:640
	s_waitcnt lgkmcnt(2)
	v_fmac_f32_e32 v10, v28, v188
	v_fmac_f32_e32 v96, v29, v189
	v_fmac_f32_e32 v10, v30, v190
	v_fmac_f32_e32 v96, v31, v191
	ds_read_b128 v[28:31], v7 offset:656
	s_waitcnt lgkmcnt(2)
	v_fmac_f32_e32 v10, v2, v192
	v_fmac_f32_e32 v96, v3, v193
	v_fmac_f32_e32 v10, v4, v196
	v_fmac_f32_e32 v96, v5, v197
	ds_read_b128 v[2:5], v7 offset:672
	s_waitcnt lgkmcnt(2)
	v_fmac_f32_e32 v10, v24, v198
	v_fmac_f32_e32 v96, v25, v199
	v_fmac_f32_e32 v10, v26, v200
	v_fmac_f32_e32 v96, v27, v201
	ds_read_b128 v[24:27], v7 offset:688
	s_waitcnt lgkmcnt(2)
	v_fmac_f32_e32 v10, v28, v202
	v_fmac_f32_e32 v96, v29, v203
	v_fmac_f32_e32 v10, v30, v204
	v_fmac_f32_e32 v96, v31, v205
	ds_read_b128 v[28:31], v7 offset:704
	s_waitcnt lgkmcnt(2)
	v_fmac_f32_e32 v10, v2, v206
	v_fmac_f32_e32 v96, v3, v207
	v_fmac_f32_e32 v10, v4, v208
	v_fmac_f32_e32 v96, v5, v209
	ds_read_b128 v[2:5], v7 offset:720
	s_waitcnt lgkmcnt(2)
	v_fmac_f32_e32 v10, v24, v210
	v_fmac_f32_e32 v96, v25, v211
	v_fmac_f32_e32 v10, v26, v212
	v_fmac_f32_e32 v96, v27, v213
	ds_read_b128 v[24:27], v7 offset:736
	s_waitcnt lgkmcnt(2)
	v_fmac_f32_e32 v10, v28, v214
	v_fmac_f32_e32 v96, v29, v215
	v_fmac_f32_e32 v10, v30, v216
	v_fmac_f32_e32 v96, v31, v217
	ds_read_b128 v[28:31], v7 offset:752
	s_waitcnt lgkmcnt(2)
	v_fmac_f32_e32 v10, v2, v218
	v_fmac_f32_e32 v96, v3, v219
	v_fmac_f32_e32 v10, v4, v220
	v_fmac_f32_e32 v96, v5, v221
	ds_read_b128 v[2:5], v7 offset:768
	s_waitcnt lgkmcnt(2)
	v_fmac_f32_e32 v10, v24, v222
	v_fmac_f32_e32 v96, v25, v223
	v_fmac_f32_e32 v10, v26, v224
	v_fmac_f32_e32 v96, v27, v225
	ds_read_b128 v[24:27], v7 offset:784
	s_waitcnt lgkmcnt(2)
	v_fmac_f32_e32 v10, v28, v226
	v_fmac_f32_e32 v96, v29, v227
	v_fmac_f32_e32 v10, v30, v228
	v_fmac_f32_e32 v96, v31, v229
	v_add_f32_e32 v10, v10, v96
	ds_read_b128 v[28:31], v7 offset:800
	s_waitcnt lgkmcnt(2)
	v_mul_f32_e32 v11, v2, v146
	v_mul_f32_e32 v97, v3, v147
	v_fmac_f32_e32 v11, v4, v148
	v_fmac_f32_e32 v97, v5, v149
	ds_read_b128 v[2:5], v7 offset:816
	s_waitcnt lgkmcnt(2)
	v_fmac_f32_e32 v11, v24, v150
	v_fmac_f32_e32 v97, v25, v151
	v_fmac_f32_e32 v11, v26, v152
	v_fmac_f32_e32 v97, v27, v153
	ds_read_b128 v[24:27], v7 offset:832
	s_waitcnt lgkmcnt(2)
	v_fmac_f32_e32 v11, v28, v154
	v_fmac_f32_e32 v97, v29, v155
	v_fmac_f32_e32 v11, v30, v156
	v_fmac_f32_e32 v97, v31, v157
	ds_read_b128 v[28:31], v7 offset:848
	s_waitcnt lgkmcnt(2)
	v_fmac_f32_e32 v11, v2, v158
	v_fmac_f32_e32 v97, v3, v159
	v_fmac_f32_e32 v11, v4, v160
	v_fmac_f32_e32 v97, v5, v161
	ds_read_b128 v[2:5], v7 offset:864
	s_waitcnt lgkmcnt(2)
	v_fmac_f32_e32 v11, v24, v162
	v_fmac_f32_e32 v97, v25, v163
	v_fmac_f32_e32 v11, v26, v164
	v_fmac_f32_e32 v97, v27, v165
	ds_read_b128 v[24:27], v7 offset:880
	s_waitcnt lgkmcnt(2)
	v_fmac_f32_e32 v11, v28, v184
	v_fmac_f32_e32 v97, v29, v185
	v_fmac_f32_e32 v11, v30, v186
	v_fmac_f32_e32 v97, v31, v187
	ds_read_b128 v[28:31], v7 offset:896
	s_waitcnt lgkmcnt(2)
	v_fmac_f32_e32 v11, v2, v188
	v_fmac_f32_e32 v97, v3, v189
	v_fmac_f32_e32 v11, v4, v190
	v_fmac_f32_e32 v97, v5, v191
	ds_read_b128 v[2:5], v7 offset:912
	s_waitcnt lgkmcnt(2)
	v_fmac_f32_e32 v11, v24, v192
	v_fmac_f32_e32 v97, v25, v193
	v_fmac_f32_e32 v11, v26, v196
	v_fmac_f32_e32 v97, v27, v197
	ds_read_b128 v[24:27], v7 offset:928
	s_waitcnt lgkmcnt(2)
	v_fmac_f32_e32 v11, v28, v198
	v_fmac_f32_e32 v97, v29, v199
	v_fmac_f32_e32 v11, v30, v200
	v_fmac_f32_e32 v97, v31, v201
	ds_read_b128 v[28:31], v7 offset:944
	s_waitcnt lgkmcnt(2)
	v_fmac_f32_e32 v11, v2, v202
	v_fmac_f32_e32 v97, v3, v203
	v_fmac_f32_e32 v11, v4, v204
	v_fmac_f32_e32 v97, v5, v205
	ds_read_b128 v[2:5], v7 offset:960
	s_waitcnt lgkmcnt(2)
	v_fmac_f32_e32 v11, v24, v206
	v_fmac_f32_e32 v97, v25, v207
	v_fmac_f32_e32 v11, v26, v208
	v_fmac_f32_e32 v97, v27, v209
	ds_read_b128 v[24:27], v7 offset:976
	s_waitcnt lgkmcnt(2)
	v_fmac_f32_e32 v11, v28, v210
	v_fmac_f32_e32 v97, v29, v211
	v_fmac_f32_e32 v11, v30, v212
	v_fmac_f32_e32 v97, v31, v213
	ds_read_b128 v[28:31], v7 offset:992
	s_waitcnt lgkmcnt(2)
	v_fmac_f32_e32 v11, v2, v214
	v_fmac_f32_e32 v97, v3, v215
	v_fmac_f32_e32 v11, v4, v216
	v_fmac_f32_e32 v97, v5, v217
	ds_read_b128 v[2:5], v7 offset:1008
	s_waitcnt lgkmcnt(2)
; template <int MODE>
; __device__ __forceinline__ void poolconv_wave(const Ctx& C, int l, int ch, int g, int lane, float* PL) {
;     ...
; #pragma unroll 2
;     for (int k4 = 0; k4 < 16; ++k4) {
;         const float w0 = wp[(4 * k4 + 0) * 64], w1 = wp[(4 * k4 + 1) * 64], w2 = wp[(4 * k4 + 2) * 64], w3 = wp[(4 * k4 + 3) * 64];
; #pragma unroll
;         for (int i = 0; i < 16; ++i) { const f32x4 pv = *(const f32x4*)(PL + i * 64 + 4 * k4); acc[i] += pv[0] * w0 + pv[1] * w1 + pv[2] * w2 + pv[3] * w3; }
;     }
	v_fmac_f32_e32 v11, v24, v218
	v_fmac_f32_e32 v97, v25, v219
	v_fmac_f32_e32 v11, v26, v220
	v_fmac_f32_e32 v97, v27, v221
	ds_read_b128 v[24:27], v7 offset:1024
	s_waitcnt lgkmcnt(2)
	v_fmac_f32_e32 v11, v28, v222
	v_fmac_f32_e32 v97, v29, v223
	v_fmac_f32_e32 v11, v30, v224
	v_fmac_f32_e32 v97, v31, v225
	ds_read_b128 v[28:31], v7 offset:1040
	s_waitcnt lgkmcnt(2)
	v_fmac_f32_e32 v11, v2, v226
	v_fmac_f32_e32 v97, v3, v227
	v_fmac_f32_e32 v11, v4, v228
	v_fmac_f32_e32 v97, v5, v229
	v_add_f32_e32 v11, v11, v97
	ds_read_b128 v[2:5], v7 offset:1056
	s_waitcnt lgkmcnt(2)
	v_mul_f32_e32 v12, v24, v146
	v_mul_f32_e32 v96, v25, v147
	v_fmac_f32_e32 v12, v26, v148
	v_fmac_f32_e32 v96, v27, v149
	ds_read_b128 v[24:27], v7 offset:1072
	s_waitcnt lgkmcnt(2)
	v_fmac_f32_e32 v12, v28, v150
	v_fmac_f32_e32 v96, v29, v151
	v_fmac_f32_e32 v12, v30, v152
	v_fmac_f32_e32 v96, v31, v153
	ds_read_b128 v[28:31], v7 offset:1088
	s_waitcnt lgkmcnt(2)
	v_fmac_f32_e32 v12, v2, v154
	v_fmac_f32_e32 v96, v3, v155
	v_fmac_f32_e32 v12, v4, v156
	v_fmac_f32_e32 v96, v5, v157
	ds_read_b128 v[2:5], v7 offset:1104
	s_waitcnt lgkmcnt(2)
	v_fmac_f32_e32 v12, v24, v158
	v_fmac_f32_e32 v96, v25, v159
	v_fmac_f32_e32 v12, v26, v160
	v_fmac_f32_e32 v96, v27, v161
	ds_read_b128 v[24:27], v7 offset:1120
	s_waitcnt lgkmcnt(2)
	v_fmac_f32_e32 v12, v28, v162
	v_fmac_f32_e32 v96, v29, v163
	v_fmac_f32_e32 v12, v30, v164
	v_fmac_f32_e32 v96, v31, v165
	ds_read_b128 v[28:31], v7 offset:1136
	s_waitcnt lgkmcnt(2)
	v_fmac_f32_e32 v12, v2, v184
	v_fmac_f32_e32 v96, v3, v185
	v_fmac_f32_e32 v12, v4, v186
	v_fmac_f32_e32 v96, v5, v187
	ds_read_b128 v[2:5], v7 offset:1152
	s_waitcnt lgkmcnt(2)
	v_fmac_f32_e32 v12, v24, v188
	v_fmac_f32_e32 v96, v25, v189
	v_fmac_f32_e32 v12, v26, v190
	v_fmac_f32_e32 v96, v27, v191
	ds_read_b128 v[24:27], v7 offset:1168
	s_waitcnt lgkmcnt(2)
	v_fmac_f32_e32 v12, v28, v192
	v_fmac_f32_e32 v96, v29, v193
	v_fmac_f32_e32 v12, v30, v196
	v_fmac_f32_e32 v96, v31, v197
	ds_read_b128 v[28:31], v7 offset:1184
	s_waitcnt lgkmcnt(2)
	v_fmac_f32_e32 v12, v2, v198
	v_fmac_f32_e32 v96, v3, v199
	v_fmac_f32_e32 v12, v4, v200
	v_fmac_f32_e32 v96, v5, v201
	ds_read_b128 v[2:5], v7 offset:1200
	s_waitcnt lgkmcnt(2)
	v_fmac_f32_e32 v12, v24, v202
	v_fmac_f32_e32 v96, v25, v203
	v_fmac_f32_e32 v12, v26, v204
	v_fmac_f32_e32 v96, v27, v205
	ds_read_b128 v[24:27], v7 offset:1216
	s_waitcnt lgkmcnt(2)
	v_fmac_f32_e32 v12, v28, v206
	v_fmac_f32_e32 v96, v29, v207
	v_fmac_f32_e32 v12, v30, v208
	v_fmac_f32_e32 v96, v31, v209
	ds_read_b128 v[28:31], v7 offset:1232
	s_waitcnt lgkmcnt(2)
	v_fmac_f32_e32 v12, v2, v210
	v_fmac_f32_e32 v96, v3, v211
	v_fmac_f32_e32 v12, v4, v212
	v_fmac_f32_e32 v96, v5, v213
	ds_read_b128 v[2:5], v7 offset:1248
	s_waitcnt lgkmcnt(2)
	v_fmac_f32_e32 v12, v24, v214
	v_fmac_f32_e32 v96, v25, v215
	v_fmac_f32_e32 v12, v26, v216
	v_fmac_f32_e32 v96, v27, v217
	ds_read_b128 v[24:27], v7 offset:1264
	s_waitcnt lgkmcnt(2)
	v_fmac_f32_e32 v12, v28, v218
	v_fmac_f32_e32 v96, v29, v219
	v_fmac_f32_e32 v12, v30, v220
	v_fmac_f32_e32 v96, v31, v221
	ds_read_b128 v[28:31], v7 offset:1280
	s_waitcnt lgkmcnt(2)
	v_fmac_f32_e32 v12, v2, v222
	v_fmac_f32_e32 v96, v3, v223
	v_fmac_f32_e32 v12, v4, v224
	v_fmac_f32_e32 v96, v5, v225
	ds_read_b128 v[2:5], v7 offset:1296
	s_waitcnt lgkmcnt(2)
	v_fmac_f32_e32 v12, v24, v226
	v_fmac_f32_e32 v96, v25, v227
	v_fmac_f32_e32 v12, v26, v228
	v_fmac_f32_e32 v96, v27, v229
	v_add_f32_e32 v12, v12, v96
	ds_read_b128 v[24:27], v7 offset:1312
	s_waitcnt lgkmcnt(2)
	v_mul_f32_e32 v13, v28, v146
	v_mul_f32_e32 v97, v29, v147
	v_fmac_f32_e32 v13, v30, v148
	v_fmac_f32_e32 v97, v31, v149
	ds_read_b128 v[28:31], v7 offset:1328
	s_waitcnt lgkmcnt(2)
	v_fmac_f32_e32 v13, v2, v150
	v_fmac_f32_e32 v97, v3, v151
	v_fmac_f32_e32 v13, v4, v152
	v_fmac_f32_e32 v97, v5, v153
	ds_read_b128 v[2:5], v7 offset:1344
	s_waitcnt lgkmcnt(2)
	v_fmac_f32_e32 v13, v24, v154
	v_fmac_f32_e32 v97, v25, v155
	v_fmac_f32_e32 v13, v26, v156
	v_fmac_f32_e32 v97, v27, v157
	ds_read_b128 v[24:27], v7 offset:1360
	s_waitcnt lgkmcnt(2)
	v_fmac_f32_e32 v13, v28, v158
	v_fmac_f32_e32 v97, v29, v159
	v_fmac_f32_e32 v13, v30, v160
	v_fmac_f32_e32 v97, v31, v161
	ds_read_b128 v[28:31], v7 offset:1376
	s_waitcnt lgkmcnt(2)
	v_fmac_f32_e32 v13, v2, v162
	v_fmac_f32_e32 v97, v3, v163
	v_fmac_f32_e32 v13, v4, v164
	v_fmac_f32_e32 v97, v5, v165
	ds_read_b128 v[2:5], v7 offset:1392
	s_waitcnt lgkmcnt(2)
	v_fmac_f32_e32 v13, v24, v184
	v_fmac_f32_e32 v97, v25, v185
	v_fmac_f32_e32 v13, v26, v186
	v_fmac_f32_e32 v97, v27, v187
	ds_read_b128 v[24:27], v7 offset:1408
	s_waitcnt lgkmcnt(2)
	v_fmac_f32_e32 v13, v28, v188
	v_fmac_f32_e32 v97, v29, v189
	v_fmac_f32_e32 v13, v30, v190
	v_fmac_f32_e32 v97, v31, v191
	ds_read_b128 v[28:31], v7 offset:1424
	s_waitcnt lgkmcnt(2)
	v_fmac_f32_e32 v13, v2, v192
	v_fmac_f32_e32 v97, v3, v193
	v_fmac_f32_e32 v13, v4, v196
	v_fmac_f32_e32 v97, v5, v197
	ds_read_b128 v[2:5], v7 offset:1440
	s_waitcnt lgkmcnt(2)
	v_fmac_f32_e32 v13, v24, v198
	v_fmac_f32_e32 v97, v25, v199
	v_fmac_f32_e32 v13, v26, v200
	v_fmac_f32_e32 v97, v27, v201
	ds_read_b128 v[24:27], v7 offset:1456
	s_waitcnt lgkmcnt(2)
	v_fmac_f32_e32 v13, v28, v202
	v_fmac_f32_e32 v97, v29, v203
	v_fmac_f32_e32 v13, v30, v204
	v_fmac_f32_e32 v97, v31, v205
	ds_read_b128 v[28:31], v7 offset:1472
	s_waitcnt lgkmcnt(2)
	v_fmac_f32_e32 v13, v2, v206
	v_fmac_f32_e32 v97, v3, v207
	v_fmac_f32_e32 v13, v4, v208
	v_fmac_f32_e32 v97, v5, v209
	ds_read_b128 v[2:5], v7 offset:1488
	s_waitcnt lgkmcnt(2)
	v_fmac_f32_e32 v13, v24, v210
	v_fmac_f32_e32 v97, v25, v211
	v_fmac_f32_e32 v13, v26, v212
	v_fmac_f32_e32 v97, v27, v213
	ds_read_b128 v[24:27], v7 offset:1504
	s_waitcnt lgkmcnt(2)
; template <int MODE>
; __device__ __forceinline__ void poolconv_wave(const Ctx& C, int l, int ch, int g, int lane, float* PL) {
;     ...
; #pragma unroll 2
;     for (int k4 = 0; k4 < 16; ++k4) {
;         const float w0 = wp[(4 * k4 + 0) * 64], w1 = wp[(4 * k4 + 1) * 64], w2 = wp[(4 * k4 + 2) * 64], w3 = wp[(4 * k4 + 3) * 64];
; #pragma unroll
;         for (int i = 0; i < 16; ++i) { const f32x4 pv = *(const f32x4*)(PL + i * 64 + 4 * k4); acc[i] += pv[0] * w0 + pv[1] * w1 + pv[2] * w2 + pv[3] * w3; }
;     }
	v_fmac_f32_e32 v13, v28, v214
	v_fmac_f32_e32 v97, v29, v215
	v_fmac_f32_e32 v13, v30, v216
	v_fmac_f32_e32 v97, v31, v217
	ds_read_b128 v[28:31], v7 offset:1520
	s_waitcnt lgkmcnt(2)
	v_fmac_f32_e32 v13, v2, v218
	v_fmac_f32_e32 v97, v3, v219
	v_fmac_f32_e32 v13, v4, v220
	v_fmac_f32_e32 v97, v5, v221
	ds_read_b128 v[2:5], v7 offset:1536
	s_waitcnt lgkmcnt(2)
	v_fmac_f32_e32 v13, v24, v222
	v_fmac_f32_e32 v97, v25, v223
	v_fmac_f32_e32 v13, v26, v224
	v_fmac_f32_e32 v97, v27, v225
	ds_read_b128 v[24:27], v7 offset:1552
	s_waitcnt lgkmcnt(2)
	v_fmac_f32_e32 v13, v28, v226
	v_fmac_f32_e32 v97, v29, v227
	v_fmac_f32_e32 v13, v30, v228
	v_fmac_f32_e32 v97, v31, v229
	v_add_f32_e32 v13, v13, v97
	ds_read_b128 v[28:31], v7 offset:1568
	s_waitcnt lgkmcnt(2)
	v_mul_f32_e32 v14, v2, v146
	v_mul_f32_e32 v96, v3, v147
	v_fmac_f32_e32 v14, v4, v148
	v_fmac_f32_e32 v96, v5, v149
	ds_read_b128 v[2:5], v7 offset:1584
	s_waitcnt lgkmcnt(2)
	v_fmac_f32_e32 v14, v24, v150
	v_fmac_f32_e32 v96, v25, v151
	v_fmac_f32_e32 v14, v26, v152
	v_fmac_f32_e32 v96, v27, v153
	ds_read_b128 v[24:27], v7 offset:1600
	s_waitcnt lgkmcnt(2)
	v_fmac_f32_e32 v14, v28, v154
	v_fmac_f32_e32 v96, v29, v155
	v_fmac_f32_e32 v14, v30, v156
	v_fmac_f32_e32 v96, v31, v157
	ds_read_b128 v[28:31], v7 offset:1616
	s_waitcnt lgkmcnt(2)
	v_fmac_f32_e32 v14, v2, v158
	v_fmac_f32_e32 v96, v3, v159
	v_fmac_f32_e32 v14, v4, v160
	v_fmac_f32_e32 v96, v5, v161
	ds_read_b128 v[2:5], v7 offset:1632
	s_waitcnt lgkmcnt(2)
	v_fmac_f32_e32 v14, v24, v162
	v_fmac_f32_e32 v96, v25, v163
	v_fmac_f32_e32 v14, v26, v164
	v_fmac_f32_e32 v96, v27, v165
	ds_read_b128 v[24:27], v7 offset:1648
	s_waitcnt lgkmcnt(2)
	v_fmac_f32_e32 v14, v28, v184
	v_fmac_f32_e32 v96, v29, v185
	v_fmac_f32_e32 v14, v30, v186
	v_fmac_f32_e32 v96, v31, v187
	ds_read_b128 v[28:31], v7 offset:1664
	s_waitcnt lgkmcnt(2)
	v_fmac_f32_e32 v14, v2, v188
	v_fmac_f32_e32 v96, v3, v189
	v_fmac_f32_e32 v14, v4, v190
	v_fmac_f32_e32 v96, v5, v191
	ds_read_b128 v[2:5], v7 offset:1680
	s_waitcnt lgkmcnt(2)
	v_fmac_f32_e32 v14, v24, v192
	v_fmac_f32_e32 v96, v25, v193
	v_fmac_f32_e32 v14, v26, v196
	v_fmac_f32_e32 v96, v27, v197
	ds_read_b128 v[24:27], v7 offset:1696
	s_waitcnt lgkmcnt(2)
	v_fmac_f32_e32 v14, v28, v198
	v_fmac_f32_e32 v96, v29, v199
	v_fmac_f32_e32 v14, v30, v200
	v_fmac_f32_e32 v96, v31, v201
	ds_read_b128 v[28:31], v7 offset:1712
	s_waitcnt lgkmcnt(2)
	v_fmac_f32_e32 v14, v2, v202
	v_fmac_f32_e32 v96, v3, v203
	v_fmac_f32_e32 v14, v4, v204
	v_fmac_f32_e32 v96, v5, v205
	ds_read_b128 v[2:5], v7 offset:1728
	s_waitcnt lgkmcnt(2)
	v_fmac_f32_e32 v14, v24, v206
	v_fmac_f32_e32 v96, v25, v207
	v_fmac_f32_e32 v14, v26, v208
	v_fmac_f32_e32 v96, v27, v209
	ds_read_b128 v[24:27], v7 offset:1744
	s_waitcnt lgkmcnt(2)
	v_fmac_f32_e32 v14, v28, v210
	v_fmac_f32_e32 v96, v29, v211
	v_fmac_f32_e32 v14, v30, v212
	v_fmac_f32_e32 v96, v31, v213
	ds_read_b128 v[28:31], v7 offset:1760
	s_waitcnt lgkmcnt(2)
	v_fmac_f32_e32 v14, v2, v214
	v_fmac_f32_e32 v96, v3, v215
	v_fmac_f32_e32 v14, v4, v216
	v_fmac_f32_e32 v96, v5, v217
	ds_read_b128 v[2:5], v7 offset:1776
	s_waitcnt lgkmcnt(2)
	v_fmac_f32_e32 v14, v24, v218
	v_fmac_f32_e32 v96, v25, v219
	v_fmac_f32_e32 v14, v26, v220
	v_fmac_f32_e32 v96, v27, v221
	ds_read_b128 v[24:27], v7 offset:1792
	s_waitcnt lgkmcnt(2)
	v_fmac_f32_e32 v14, v28, v222
	v_fmac_f32_e32 v96, v29, v223
	v_fmac_f32_e32 v14, v30, v224
	v_fmac_f32_e32 v96, v31, v225
	ds_read_b128 v[28:31], v7 offset:1808
	s_waitcnt lgkmcnt(2)
	v_fmac_f32_e32 v14, v2, v226
	v_fmac_f32_e32 v96, v3, v227
	v_fmac_f32_e32 v14, v4, v228
	v_fmac_f32_e32 v96, v5, v229
	v_add_f32_e32 v14, v14, v96
	ds_read_b128 v[2:5], v7 offset:1824
	s_waitcnt lgkmcnt(2)
	v_mul_f32_e32 v15, v24, v146
	v_mul_f32_e32 v97, v25, v147
	v_fmac_f32_e32 v15, v26, v148
	v_fmac_f32_e32 v97, v27, v149
	ds_read_b128 v[24:27], v7 offset:1840
	s_waitcnt lgkmcnt(2)
	v_fmac_f32_e32 v15, v28, v150
	v_fmac_f32_e32 v97, v29, v151
	v_fmac_f32_e32 v15, v30, v152
	v_fmac_f32_e32 v97, v31, v153
	ds_read_b128 v[28:31], v7 offset:1856
	s_waitcnt lgkmcnt(2)
	v_fmac_f32_e32 v15, v2, v154
	v_fmac_f32_e32 v97, v3, v155
	v_fmac_f32_e32 v15, v4, v156
	v_fmac_f32_e32 v97, v5, v157
	ds_read_b128 v[2:5], v7 offset:1872
	s_waitcnt lgkmcnt(2)
	v_fmac_f32_e32 v15, v24, v158
	v_fmac_f32_e32 v97, v25, v159
	v_fmac_f32_e32 v15, v26, v160
	v_fmac_f32_e32 v97, v27, v161
	ds_read_b128 v[24:27], v7 offset:1888
	s_waitcnt lgkmcnt(2)
	v_fmac_f32_e32 v15, v28, v162
	v_fmac_f32_e32 v97, v29, v163
	v_fmac_f32_e32 v15, v30, v164
	v_fmac_f32_e32 v97, v31, v165
	ds_read_b128 v[28:31], v7 offset:1904
	s_waitcnt lgkmcnt(2)
	v_fmac_f32_e32 v15, v2, v184
	v_fmac_f32_e32 v97, v3, v185
	v_fmac_f32_e32 v15, v4, v186
	v_fmac_f32_e32 v97, v5, v187
	ds_read_b128 v[2:5], v7 offset:1920
	s_waitcnt lgkmcnt(2)
	v_fmac_f32_e32 v15, v24, v188
	v_fmac_f32_e32 v97, v25, v189
	v_fmac_f32_e32 v15, v26, v190
	v_fmac_f32_e32 v97, v27, v191
	ds_read_b128 v[24:27], v7 offset:1936
	s_waitcnt lgkmcnt(2)
	v_fmac_f32_e32 v15, v28, v192
	v_fmac_f32_e32 v97, v29, v193
	v_fmac_f32_e32 v15, v30, v196
	v_fmac_f32_e32 v97, v31, v197
	ds_read_b128 v[28:31], v7 offset:1952
	s_waitcnt lgkmcnt(2)
	v_fmac_f32_e32 v15, v2, v198
	v_fmac_f32_e32 v97, v3, v199
	v_fmac_f32_e32 v15, v4, v200
	v_fmac_f32_e32 v97, v5, v201
	ds_read_b128 v[2:5], v7 offset:1968
	s_waitcnt lgkmcnt(2)
	v_fmac_f32_e32 v15, v24, v202
	v_fmac_f32_e32 v97, v25, v203
	v_fmac_f32_e32 v15, v26, v204
	v_fmac_f32_e32 v97, v27, v205
	ds_read_b128 v[24:27], v7 offset:1984
	s_waitcnt lgkmcnt(2)
	v_fmac_f32_e32 v15, v28, v206
	v_fmac_f32_e32 v97, v29, v207
	v_fmac_f32_e32 v15, v30, v208
	v_fmac_f32_e32 v97, v31, v209
	ds_read_b128 v[28:31], v7 offset:2000
	s_waitcnt lgkmcnt(2)
; template <int MODE>
; __device__ __forceinline__ void poolconv_wave(const Ctx& C, int l, int ch, int g, int lane, float* PL) {
;     ...
; #pragma unroll 2
;     for (int k4 = 0; k4 < 16; ++k4) {
;         const float w0 = wp[(4 * k4 + 0) * 64], w1 = wp[(4 * k4 + 1) * 64], w2 = wp[(4 * k4 + 2) * 64], w3 = wp[(4 * k4 + 3) * 64];
; #pragma unroll
;         for (int i = 0; i < 16; ++i) { const f32x4 pv = *(const f32x4*)(PL + i * 64 + 4 * k4); acc[i] += pv[0] * w0 + pv[1] * w1 + pv[2] * w2 + pv[3] * w3; }
;     }
	v_fmac_f32_e32 v15, v2, v210
	v_fmac_f32_e32 v97, v3, v211
	v_fmac_f32_e32 v15, v4, v212
	v_fmac_f32_e32 v97, v5, v213
	ds_read_b128 v[2:5], v7 offset:2016
	s_waitcnt lgkmcnt(2)
	v_fmac_f32_e32 v15, v24, v214
	v_fmac_f32_e32 v97, v25, v215
	v_fmac_f32_e32 v15, v26, v216
	v_fmac_f32_e32 v97, v27, v217
	ds_read_b128 v[24:27], v7 offset:2032
	s_waitcnt lgkmcnt(2)
	v_fmac_f32_e32 v15, v28, v218
	v_fmac_f32_e32 v97, v29, v219
	v_fmac_f32_e32 v15, v30, v220
	v_fmac_f32_e32 v97, v31, v221
	ds_read_b128 v[28:31], v7 offset:2048
	s_waitcnt lgkmcnt(2)
	v_fmac_f32_e32 v15, v2, v222
	v_fmac_f32_e32 v97, v3, v223
	v_fmac_f32_e32 v15, v4, v224
	v_fmac_f32_e32 v97, v5, v225
	ds_read_b128 v[2:5], v7 offset:2064
	s_waitcnt lgkmcnt(2)
	v_fmac_f32_e32 v15, v24, v226
	v_fmac_f32_e32 v97, v25, v227
	v_fmac_f32_e32 v15, v26, v228
	v_fmac_f32_e32 v97, v27, v229
	v_add_f32_e32 v15, v15, v97
	ds_read_b128 v[24:27], v7 offset:2080
	s_waitcnt lgkmcnt(2)
	v_mul_f32_e32 v16, v28, v146
	v_mul_f32_e32 v96, v29, v147
	v_fmac_f32_e32 v16, v30, v148
	v_fmac_f32_e32 v96, v31, v149
	ds_read_b128 v[28:31], v7 offset:2096
	s_waitcnt lgkmcnt(2)
	v_fmac_f32_e32 v16, v2, v150
	v_fmac_f32_e32 v96, v3, v151
	v_fmac_f32_e32 v16, v4, v152
	v_fmac_f32_e32 v96, v5, v153
	ds_read_b128 v[2:5], v7 offset:2112
	s_waitcnt lgkmcnt(2)
	v_fmac_f32_e32 v16, v24, v154
	v_fmac_f32_e32 v96, v25, v155
	v_fmac_f32_e32 v16, v26, v156
	v_fmac_f32_e32 v96, v27, v157
	ds_read_b128 v[24:27], v7 offset:2128
	s_waitcnt lgkmcnt(2)
	v_fmac_f32_e32 v16, v28, v158
	v_fmac_f32_e32 v96, v29, v159
	v_fmac_f32_e32 v16, v30, v160
	v_fmac_f32_e32 v96, v31, v161
	ds_read_b128 v[28:31], v7 offset:2144
	s_waitcnt lgkmcnt(2)
	v_fmac_f32_e32 v16, v2, v162
	v_fmac_f32_e32 v96, v3, v163
	v_fmac_f32_e32 v16, v4, v164
	v_fmac_f32_e32 v96, v5, v165
	ds_read_b128 v[2:5], v7 offset:2160
	s_waitcnt lgkmcnt(2)
	v_fmac_f32_e32 v16, v24, v184
	v_fmac_f32_e32 v96, v25, v185
	v_fmac_f32_e32 v16, v26, v186
	v_fmac_f32_e32 v96, v27, v187
	ds_read_b128 v[24:27], v7 offset:2176
	s_waitcnt lgkmcnt(2)
	v_fmac_f32_e32 v16, v28, v188
	v_fmac_f32_e32 v96, v29, v189
	v_fmac_f32_e32 v16, v30, v190
	v_fmac_f32_e32 v96, v31, v191
	ds_read_b128 v[28:31], v7 offset:2192
	s_waitcnt lgkmcnt(2)
	v_fmac_f32_e32 v16, v2, v192
	v_fmac_f32_e32 v96, v3, v193
	v_fmac_f32_e32 v16, v4, v196
	v_fmac_f32_e32 v96, v5, v197
	ds_read_b128 v[2:5], v7 offset:2208
	s_waitcnt lgkmcnt(2)
	v_fmac_f32_e32 v16, v24, v198
	v_fmac_f32_e32 v96, v25, v199
	v_fmac_f32_e32 v16, v26, v200
	v_fmac_f32_e32 v96, v27, v201
	ds_read_b128 v[24:27], v7 offset:2224
	s_waitcnt lgkmcnt(2)
	v_fmac_f32_e32 v16, v28, v202
	v_fmac_f32_e32 v96, v29, v203
	v_fmac_f32_e32 v16, v30, v204
	v_fmac_f32_e32 v96, v31, v205
	ds_read_b128 v[28:31], v7 offset:2240
	s_waitcnt lgkmcnt(2)
	v_fmac_f32_e32 v16, v2, v206
	v_fmac_f32_e32 v96, v3, v207
	v_fmac_f32_e32 v16, v4, v208
	v_fmac_f32_e32 v96, v5, v209
	ds_read_b128 v[2:5], v7 offset:2256
	s_waitcnt lgkmcnt(2)
	v_fmac_f32_e32 v16, v24, v210
	v_fmac_f32_e32 v96, v25, v211
	v_fmac_f32_e32 v16, v26, v212
	v_fmac_f32_e32 v96, v27, v213
	ds_read_b128 v[24:27], v7 offset:2272
	s_waitcnt lgkmcnt(2)
	v_fmac_f32_e32 v16, v28, v214
	v_fmac_f32_e32 v96, v29, v215
	v_fmac_f32_e32 v16, v30, v216
	v_fmac_f32_e32 v96, v31, v217
	ds_read_b128 v[28:31], v7 offset:2288
	s_waitcnt lgkmcnt(2)
	v_fmac_f32_e32 v16, v2, v218
	v_fmac_f32_e32 v96, v3, v219
	v_fmac_f32_e32 v16, v4, v220
	v_fmac_f32_e32 v96, v5, v221
	ds_read_b128 v[2:5], v7 offset:2304
	s_waitcnt lgkmcnt(2)
	v_fmac_f32_e32 v16, v24, v222
	v_fmac_f32_e32 v96, v25, v223
	v_fmac_f32_e32 v16, v26, v224
	v_fmac_f32_e32 v96, v27, v225
	ds_read_b128 v[24:27], v7 offset:2320
	s_waitcnt lgkmcnt(2)
	v_fmac_f32_e32 v16, v28, v226
	v_fmac_f32_e32 v96, v29, v227
	v_fmac_f32_e32 v16, v30, v228
	v_fmac_f32_e32 v96, v31, v229
	v_add_f32_e32 v16, v16, v96
	ds_read_b128 v[28:31], v7 offset:2336
	s_waitcnt lgkmcnt(2)
	v_mul_f32_e32 v17, v2, v146
	v_mul_f32_e32 v97, v3, v147
	v_fmac_f32_e32 v17, v4, v148
	v_fmac_f32_e32 v97, v5, v149
	ds_read_b128 v[2:5], v7 offset:2352
	s_waitcnt lgkmcnt(2)
	v_fmac_f32_e32 v17, v24, v150
	v_fmac_f32_e32 v97, v25, v151
	v_fmac_f32_e32 v17, v26, v152
	v_fmac_f32_e32 v97, v27, v153
	ds_read_b128 v[24:27], v7 offset:2368
	s_waitcnt lgkmcnt(2)
	v_fmac_f32_e32 v17, v28, v154
	v_fmac_f32_e32 v97, v29, v155
	v_fmac_f32_e32 v17, v30, v156
	v_fmac_f32_e32 v97, v31, v157
	ds_read_b128 v[28:31], v7 offset:2384
	s_waitcnt lgkmcnt(2)
	v_fmac_f32_e32 v17, v2, v158
	v_fmac_f32_e32 v97, v3, v159
	v_fmac_f32_e32 v17, v4, v160
	v_fmac_f32_e32 v97, v5, v161
	ds_read_b128 v[2:5], v7 offset:2400
	s_waitcnt lgkmcnt(2)
	v_fmac_f32_e32 v17, v24, v162
	v_fmac_f32_e32 v97, v25, v163
	v_fmac_f32_e32 v17, v26, v164
	v_fmac_f32_e32 v97, v27, v165
	ds_read_b128 v[24:27], v7 offset:2416
	s_waitcnt lgkmcnt(2)
	v_fmac_f32_e32 v17, v28, v184
	v_fmac_f32_e32 v97, v29, v185
	v_fmac_f32_e32 v17, v30, v186
	v_fmac_f32_e32 v97, v31, v187
	ds_read_b128 v[28:31], v7 offset:2432
	s_waitcnt lgkmcnt(2)
	v_fmac_f32_e32 v17, v2, v188
	v_fmac_f32_e32 v97, v3, v189
	v_fmac_f32_e32 v17, v4, v190
	v_fmac_f32_e32 v97, v5, v191
	ds_read_b128 v[2:5], v7 offset:2448
	s_waitcnt lgkmcnt(2)
	v_fmac_f32_e32 v17, v24, v192
	v_fmac_f32_e32 v97, v25, v193
	v_fmac_f32_e32 v17, v26, v196
	v_fmac_f32_e32 v97, v27, v197
	ds_read_b128 v[24:27], v7 offset:2464
	s_waitcnt lgkmcnt(2)
	v_fmac_f32_e32 v17, v28, v198
	v_fmac_f32_e32 v97, v29, v199
	v_fmac_f32_e32 v17, v30, v200
	v_fmac_f32_e32 v97, v31, v201
	ds_read_b128 v[28:31], v7 offset:2480
	s_waitcnt lgkmcnt(2)
	v_fmac_f32_e32 v17, v2, v202
	v_fmac_f32_e32 v97, v3, v203
	v_fmac_f32_e32 v17, v4, v204
	v_fmac_f32_e32 v97, v5, v205
	ds_read_b128 v[2:5], v7 offset:2496
	s_waitcnt lgkmcnt(2)
; template <int MODE>
; __device__ __forceinline__ void poolconv_wave(const Ctx& C, int l, int ch, int g, int lane, float* PL) {
;     ...
; #pragma unroll 2
;     for (int k4 = 0; k4 < 16; ++k4) {
;         const float w0 = wp[(4 * k4 + 0) * 64], w1 = wp[(4 * k4 + 1) * 64], w2 = wp[(4 * k4 + 2) * 64], w3 = wp[(4 * k4 + 3) * 64];
; #pragma unroll
;         for (int i = 0; i < 16; ++i) { const f32x4 pv = *(const f32x4*)(PL + i * 64 + 4 * k4); acc[i] += pv[0] * w0 + pv[1] * w1 + pv[2] * w2 + pv[3] * w3; }
;     }
	v_fmac_f32_e32 v17, v24, v206
	v_fmac_f32_e32 v97, v25, v207
	v_fmac_f32_e32 v17, v26, v208
	v_fmac_f32_e32 v97, v27, v209
	ds_read_b128 v[24:27], v7 offset:2512
	s_waitcnt lgkmcnt(2)
	v_fmac_f32_e32 v17, v28, v210
	v_fmac_f32_e32 v97, v29, v211
	v_fmac_f32_e32 v17, v30, v212
	v_fmac_f32_e32 v97, v31, v213
	ds_read_b128 v[28:31], v7 offset:2528
	s_waitcnt lgkmcnt(2)
	v_fmac_f32_e32 v17, v2, v214
	v_fmac_f32_e32 v97, v3, v215
	v_fmac_f32_e32 v17, v4, v216
	v_fmac_f32_e32 v97, v5, v217
	ds_read_b128 v[2:5], v7 offset:2544
	s_waitcnt lgkmcnt(2)
	v_fmac_f32_e32 v17, v24, v218
	v_fmac_f32_e32 v97, v25, v219
	v_fmac_f32_e32 v17, v26, v220
	v_fmac_f32_e32 v97, v27, v221
	ds_read_b128 v[24:27], v7 offset:2560
	s_waitcnt lgkmcnt(2)
	v_fmac_f32_e32 v17, v28, v222
	v_fmac_f32_e32 v97, v29, v223
	v_fmac_f32_e32 v17, v30, v224
	v_fmac_f32_e32 v97, v31, v225
	ds_read_b128 v[28:31], v7 offset:2576
	s_waitcnt lgkmcnt(2)
	v_fmac_f32_e32 v17, v2, v226
	v_fmac_f32_e32 v97, v3, v227
	v_fmac_f32_e32 v17, v4, v228
	v_fmac_f32_e32 v97, v5, v229
	v_add_f32_e32 v17, v17, v97
	ds_read_b128 v[2:5], v7 offset:2592
	s_waitcnt lgkmcnt(2)
	v_mul_f32_e32 v18, v24, v146
	v_mul_f32_e32 v96, v25, v147
	v_fmac_f32_e32 v18, v26, v148
	v_fmac_f32_e32 v96, v27, v149
	ds_read_b128 v[24:27], v7 offset:2608
	s_waitcnt lgkmcnt(2)
	v_fmac_f32_e32 v18, v28, v150
	v_fmac_f32_e32 v96, v29, v151
	v_fmac_f32_e32 v18, v30, v152
	v_fmac_f32_e32 v96, v31, v153
	ds_read_b128 v[28:31], v7 offset:2624
	s_waitcnt lgkmcnt(2)
	v_fmac_f32_e32 v18, v2, v154
	v_fmac_f32_e32 v96, v3, v155
	v_fmac_f32_e32 v18, v4, v156
	v_fmac_f32_e32 v96, v5, v157
	ds_read_b128 v[2:5], v7 offset:2640
	s_waitcnt lgkmcnt(2)
	v_fmac_f32_e32 v18, v24, v158
	v_fmac_f32_e32 v96, v25, v159
	v_fmac_f32_e32 v18, v26, v160
	v_fmac_f32_e32 v96, v27, v161
	ds_read_b128 v[24:27], v7 offset:2656
	s_waitcnt lgkmcnt(2)
	v_fmac_f32_e32 v18, v28, v162
	v_fmac_f32_e32 v96, v29, v163
	v_fmac_f32_e32 v18, v30, v164
	v_fmac_f32_e32 v96, v31, v165
	ds_read_b128 v[28:31], v7 offset:2672
	s_waitcnt lgkmcnt(2)
	v_fmac_f32_e32 v18, v2, v184
	v_fmac_f32_e32 v96, v3, v185
	v_fmac_f32_e32 v18, v4, v186
	v_fmac_f32_e32 v96, v5, v187
	ds_read_b128 v[2:5], v7 offset:2688
	s_waitcnt lgkmcnt(2)
	v_fmac_f32_e32 v18, v24, v188
	v_fmac_f32_e32 v96, v25, v189
	v_fmac_f32_e32 v18, v26, v190
	v_fmac_f32_e32 v96, v27, v191
	ds_read_b128 v[24:27], v7 offset:2704
	s_waitcnt lgkmcnt(2)
	v_fmac_f32_e32 v18, v28, v192
	v_fmac_f32_e32 v96, v29, v193
	v_fmac_f32_e32 v18, v30, v196
	v_fmac_f32_e32 v96, v31, v197
	ds_read_b128 v[28:31], v7 offset:2720
	s_waitcnt lgkmcnt(2)
	v_fmac_f32_e32 v18, v2, v198
	v_fmac_f32_e32 v96, v3, v199
	v_fmac_f32_e32 v18, v4, v200
	v_fmac_f32_e32 v96, v5, v201
	ds_read_b128 v[2:5], v7 offset:2736
	s_waitcnt lgkmcnt(2)
	v_fmac_f32_e32 v18, v24, v202
	v_fmac_f32_e32 v96, v25, v203
	v_fmac_f32_e32 v18, v26, v204
	v_fmac_f32_e32 v96, v27, v205
	ds_read_b128 v[24:27], v7 offset:2752
	s_waitcnt lgkmcnt(2)
	v_fmac_f32_e32 v18, v28, v206
	v_fmac_f32_e32 v96, v29, v207
	v_fmac_f32_e32 v18, v30, v208
	v_fmac_f32_e32 v96, v31, v209
	ds_read_b128 v[28:31], v7 offset:2768
	s_waitcnt lgkmcnt(2)
	v_fmac_f32_e32 v18, v2, v210
	v_fmac_f32_e32 v96, v3, v211
	v_fmac_f32_e32 v18, v4, v212
	v_fmac_f32_e32 v96, v5, v213
	ds_read_b128 v[2:5], v7 offset:2784
	s_waitcnt lgkmcnt(2)
	v_fmac_f32_e32 v18, v24, v214
	v_fmac_f32_e32 v96, v25, v215
	v_fmac_f32_e32 v18, v26, v216
	v_fmac_f32_e32 v96, v27, v217
	ds_read_b128 v[24:27], v7 offset:2800
	s_waitcnt lgkmcnt(2)
	v_fmac_f32_e32 v18, v28, v218
	v_fmac_f32_e32 v96, v29, v219
	v_fmac_f32_e32 v18, v30, v220
	v_fmac_f32_e32 v96, v31, v221
	ds_read_b128 v[28:31], v7 offset:2816
	s_waitcnt lgkmcnt(2)
	v_fmac_f32_e32 v18, v2, v222
	v_fmac_f32_e32 v96, v3, v223
	v_fmac_f32_e32 v18, v4, v224
	v_fmac_f32_e32 v96, v5, v225
	ds_read_b128 v[2:5], v7 offset:2832
	s_waitcnt lgkmcnt(2)
	v_fmac_f32_e32 v18, v24, v226
	v_fmac_f32_e32 v96, v25, v227
	v_fmac_f32_e32 v18, v26, v228
	v_fmac_f32_e32 v96, v27, v229
	v_add_f32_e32 v18, v18, v96
	ds_read_b128 v[24:27], v7 offset:2848
	s_waitcnt lgkmcnt(2)
	v_mul_f32_e32 v19, v28, v146
	v_mul_f32_e32 v97, v29, v147
	v_fmac_f32_e32 v19, v30, v148
	v_fmac_f32_e32 v97, v31, v149
	ds_read_b128 v[28:31], v7 offset:2864
	s_waitcnt lgkmcnt(2)
	v_fmac_f32_e32 v19, v2, v150
	v_fmac_f32_e32 v97, v3, v151
	v_fmac_f32_e32 v19, v4, v152
	v_fmac_f32_e32 v97, v5, v153
	ds_read_b128 v[2:5], v7 offset:2880
	s_waitcnt lgkmcnt(2)
	v_fmac_f32_e32 v19, v24, v154
	v_fmac_f32_e32 v97, v25, v155
	v_fmac_f32_e32 v19, v26, v156
	v_fmac_f32_e32 v97, v27, v157
	ds_read_b128 v[24:27], v7 offset:2896
	s_waitcnt lgkmcnt(2)
	v_fmac_f32_e32 v19, v28, v158
	v_fmac_f32_e32 v97, v29, v159
	v_fmac_f32_e32 v19, v30, v160
	v_fmac_f32_e32 v97, v31, v161
	ds_read_b128 v[28:31], v7 offset:2912
	s_waitcnt lgkmcnt(2)
	v_fmac_f32_e32 v19, v2, v162
	v_fmac_f32_e32 v97, v3, v163
	v_fmac_f32_e32 v19, v4, v164
	v_fmac_f32_e32 v97, v5, v165
	ds_read_b128 v[2:5], v7 offset:2928
	s_waitcnt lgkmcnt(2)
	v_fmac_f32_e32 v19, v24, v184
	v_fmac_f32_e32 v97, v25, v185
	v_fmac_f32_e32 v19, v26, v186
	v_fmac_f32_e32 v97, v27, v187
	ds_read_b128 v[24:27], v7 offset:2944
	s_waitcnt lgkmcnt(2)
	v_fmac_f32_e32 v19, v28, v188
	v_fmac_f32_e32 v97, v29, v189
	v_fmac_f32_e32 v19, v30, v190
	v_fmac_f32_e32 v97, v31, v191
	ds_read_b128 v[28:31], v7 offset:2960
	s_waitcnt lgkmcnt(2)
	v_fmac_f32_e32 v19, v2, v192
	v_fmac_f32_e32 v97, v3, v193
	v_fmac_f32_e32 v19, v4, v196
	v_fmac_f32_e32 v97, v5, v197
	ds_read_b128 v[2:5], v7 offset:2976
	s_waitcnt lgkmcnt(2)
	v_fmac_f32_e32 v19, v24, v198
	v_fmac_f32_e32 v97, v25, v199
	v_fmac_f32_e32 v19, v26, v200
	v_fmac_f32_e32 v97, v27, v201
	ds_read_b128 v[24:27], v7 offset:2992
	s_waitcnt lgkmcnt(2)
; template <int MODE>
; __device__ __forceinline__ void poolconv_wave(const Ctx& C, int l, int ch, int g, int lane, float* PL) {
;     ...
;     for (int k4 = 0; k4 < 16; ++k4) {
;         const float w0 = wp[(4 * k4 + 0) * 64], w1 = wp[(4 * k4 + 1) * 64], w2 = wp[(4 * k4 + 2) * 64], w3 = wp[(4 * k4 + 3) * 64];
; #pragma unroll
;         for (int i = 0; i < 16; ++i) { const f32x4 pv = *(const f32x4*)(PL + i * 64 + 4 * k4); acc[i] += pv[0] * w0 + pv[1] * w1 + pv[2] * w2 + pv[3] * w3; }
	v_fmac_f32_e32 v19, v28, v202
	v_fmac_f32_e32 v97, v29, v203
	v_fmac_f32_e32 v19, v30, v204
	v_fmac_f32_e32 v97, v31, v205
	ds_read_b128 v[28:31], v7 offset:3008
	s_waitcnt lgkmcnt(2)
	v_fmac_f32_e32 v19, v2, v206
	v_fmac_f32_e32 v97, v3, v207
	v_fmac_f32_e32 v19, v4, v208
	v_fmac_f32_e32 v97, v5, v209
	ds_read_b128 v[2:5], v7 offset:3024
	s_waitcnt lgkmcnt(2)
	v_fmac_f32_e32 v19, v24, v210
	v_fmac_f32_e32 v97, v25, v211
	v_fmac_f32_e32 v19, v26, v212
	v_fmac_f32_e32 v97, v27, v213
	ds_read_b128 v[24:27], v7 offset:3040
	s_waitcnt lgkmcnt(2)
	v_fmac_f32_e32 v19, v28, v214
	v_fmac_f32_e32 v97, v29, v215
	v_fmac_f32_e32 v19, v30, v216
	v_fmac_f32_e32 v97, v31, v217
	ds_read_b128 v[28:31], v7 offset:3056
	s_waitcnt lgkmcnt(2)
	v_fmac_f32_e32 v19, v2, v218
	v_fmac_f32_e32 v97, v3, v219
	v_fmac_f32_e32 v19, v4, v220
	v_fmac_f32_e32 v97, v5, v221
	ds_read_b128 v[2:5], v7 offset:3072
	s_waitcnt lgkmcnt(2)
	v_fmac_f32_e32 v19, v24, v222
	v_fmac_f32_e32 v97, v25, v223
	v_fmac_f32_e32 v19, v26, v224
	v_fmac_f32_e32 v97, v27, v225
	ds_read_b128 v[24:27], v7 offset:3088
	s_waitcnt lgkmcnt(2)
	v_fmac_f32_e32 v19, v28, v226
	v_fmac_f32_e32 v97, v29, v227
	v_fmac_f32_e32 v19, v30, v228
	v_fmac_f32_e32 v97, v31, v229
	v_add_f32_e32 v19, v19, v97
	ds_read_b128 v[28:31], v7 offset:3104
	s_waitcnt lgkmcnt(2)
	v_mul_f32_e32 v20, v2, v146
	v_mul_f32_e32 v96, v3, v147
	v_fmac_f32_e32 v20, v4, v148
	v_fmac_f32_e32 v96, v5, v149
	ds_read_b128 v[2:5], v7 offset:3120
	s_waitcnt lgkmcnt(2)
	v_fmac_f32_e32 v20, v24, v150
	v_fmac_f32_e32 v96, v25, v151
	v_fmac_f32_e32 v20, v26, v152
	v_fmac_f32_e32 v96, v27, v153
	ds_read_b128 v[24:27], v7 offset:3136
	s_waitcnt lgkmcnt(2)
	v_fmac_f32_e32 v20, v28, v154
	v_fmac_f32_e32 v96, v29, v155
	v_fmac_f32_e32 v20, v30, v156
	v_fmac_f32_e32 v96, v31, v157
	ds_read_b128 v[28:31], v7 offset:3152
	s_waitcnt lgkmcnt(2)
	v_fmac_f32_e32 v20, v2, v158
	v_fmac_f32_e32 v96, v3, v159
	v_fmac_f32_e32 v20, v4, v160
	v_fmac_f32_e32 v96, v5, v161
	ds_read_b128 v[2:5], v7 offset:3168
	s_waitcnt lgkmcnt(2)
	v_fmac_f32_e32 v20, v24, v162
	v_fmac_f32_e32 v96, v25, v163
	v_fmac_f32_e32 v20, v26, v164
	v_fmac_f32_e32 v96, v27, v165
	ds_read_b128 v[24:27], v7 offset:3184
	s_waitcnt lgkmcnt(2)
	v_fmac_f32_e32 v20, v28, v184
	v_fmac_f32_e32 v96, v29, v185
	v_fmac_f32_e32 v20, v30, v186
	v_fmac_f32_e32 v96, v31, v187
	ds_read_b128 v[28:31], v7 offset:3200
	s_waitcnt lgkmcnt(2)
	v_fmac_f32_e32 v20, v2, v188
	v_fmac_f32_e32 v96, v3, v189
	v_fmac_f32_e32 v20, v4, v190
	v_fmac_f32_e32 v96, v5, v191
	ds_read_b128 v[2:5], v7 offset:3216
	s_waitcnt lgkmcnt(2)
	v_fmac_f32_e32 v20, v24, v192
	v_fmac_f32_e32 v96, v25, v193
	v_fmac_f32_e32 v20, v26, v196
	v_fmac_f32_e32 v96, v27, v197
	ds_read_b128 v[24:27], v7 offset:3232
	s_waitcnt lgkmcnt(2)
	v_fmac_f32_e32 v20, v28, v198
	v_fmac_f32_e32 v96, v29, v199
	v_fmac_f32_e32 v20, v30, v200
	v_fmac_f32_e32 v96, v31, v201
	ds_read_b128 v[28:31], v7 offset:3248
	s_waitcnt lgkmcnt(2)
	v_fmac_f32_e32 v20, v2, v202
	v_fmac_f32_e32 v96, v3, v203
	v_fmac_f32_e32 v20, v4, v204
	v_fmac_f32_e32 v96, v5, v205
	ds_read_b128 v[2:5], v7 offset:3264
	s_waitcnt lgkmcnt(2)
	v_fmac_f32_e32 v20, v24, v206
	v_fmac_f32_e32 v96, v25, v207
	v_fmac_f32_e32 v20, v26, v208
	v_fmac_f32_e32 v96, v27, v209
	ds_read_b128 v[24:27], v7 offset:3280
	s_waitcnt lgkmcnt(2)
	v_fmac_f32_e32 v20, v28, v210
	v_fmac_f32_e32 v96, v29, v211
	v_fmac_f32_e32 v20, v30, v212
	v_fmac_f32_e32 v96, v31, v213
	ds_read_b128 v[28:31], v7 offset:3296
	s_waitcnt lgkmcnt(2)
	v_fmac_f32_e32 v20, v2, v214
	v_fmac_f32_e32 v96, v3, v215
	v_fmac_f32_e32 v20, v4, v216
	v_fmac_f32_e32 v96, v5, v217
	ds_read_b128 v[2:5], v7 offset:3312
	s_waitcnt lgkmcnt(2)
	v_fmac_f32_e32 v20, v24, v218
	v_fmac_f32_e32 v96, v25, v219
	v_fmac_f32_e32 v20, v26, v220
	v_fmac_f32_e32 v96, v27, v221
	ds_read_b128 v[24:27], v7 offset:3328
	s_waitcnt lgkmcnt(2)
	v_fmac_f32_e32 v20, v28, v222
	v_fmac_f32_e32 v96, v29, v223
	v_fmac_f32_e32 v20, v30, v224
	v_fmac_f32_e32 v96, v31, v225
	ds_read_b128 v[28:31], v7 offset:3344
	s_waitcnt lgkmcnt(2)
	v_fmac_f32_e32 v20, v2, v226
	v_fmac_f32_e32 v96, v3, v227
	v_fmac_f32_e32 v20, v4, v228
	v_fmac_f32_e32 v96, v5, v229
	v_add_f32_e32 v20, v20, v96
	ds_read_b128 v[2:5], v7 offset:3360
	s_waitcnt lgkmcnt(2)
	v_mul_f32_e32 v21, v24, v146
	v_mul_f32_e32 v97, v25, v147
	v_fmac_f32_e32 v21, v26, v148
	v_fmac_f32_e32 v97, v27, v149
	ds_read_b128 v[24:27], v7 offset:3376
	s_waitcnt lgkmcnt(2)
	v_fmac_f32_e32 v21, v28, v150
	v_fmac_f32_e32 v97, v29, v151
	v_fmac_f32_e32 v21, v30, v152
	v_fmac_f32_e32 v97, v31, v153
	ds_read_b128 v[28:31], v7 offset:3392
	s_waitcnt lgkmcnt(2)
	v_fmac_f32_e32 v21, v2, v154
	v_fmac_f32_e32 v97, v3, v155
	v_fmac_f32_e32 v21, v4, v156
	v_fmac_f32_e32 v97, v5, v157
	ds_read_b128 v[2:5], v7 offset:3408
	s_waitcnt lgkmcnt(2)
	v_fmac_f32_e32 v21, v24, v158
	v_fmac_f32_e32 v97, v25, v159
	v_fmac_f32_e32 v21, v26, v160
	v_fmac_f32_e32 v97, v27, v161
	ds_read_b128 v[24:27], v7 offset:3424
	s_waitcnt lgkmcnt(2)
	v_fmac_f32_e32 v21, v28, v162
	v_fmac_f32_e32 v97, v29, v163
	v_fmac_f32_e32 v21, v30, v164
	v_fmac_f32_e32 v97, v31, v165
	ds_read_b128 v[28:31], v7 offset:3440
	s_waitcnt lgkmcnt(2)
	v_fmac_f32_e32 v21, v2, v184
	v_fmac_f32_e32 v97, v3, v185
	v_fmac_f32_e32 v21, v4, v186
	v_fmac_f32_e32 v97, v5, v187
	ds_read_b128 v[2:5], v7 offset:3456
	s_waitcnt lgkmcnt(2)
	v_fmac_f32_e32 v21, v24, v188
	v_fmac_f32_e32 v97, v25, v189
	v_fmac_f32_e32 v21, v26, v190
	v_fmac_f32_e32 v97, v27, v191
	ds_read_b128 v[24:27], v7 offset:3472
	s_waitcnt lgkmcnt(2)
	v_fmac_f32_e32 v21, v28, v192
	v_fmac_f32_e32 v97, v29, v193
	v_fmac_f32_e32 v21, v30, v196
	v_fmac_f32_e32 v97, v31, v197
	ds_read_b128 v[28:31], v7 offset:3488
	s_waitcnt lgkmcnt(2)
; template <int MODE>
; __device__ __forceinline__ void poolconv_wave(const Ctx& C, int l, int ch, int g, int lane, float* PL) {
;     ...
;     for (int k4 = 0; k4 < 16; ++k4) {
;         const float w0 = wp[(4 * k4 + 0) * 64], w1 = wp[(4 * k4 + 1) * 64], w2 = wp[(4 * k4 + 2) * 64], w3 = wp[(4 * k4 + 3) * 64];
; #pragma unroll
;         for (int i = 0; i < 16; ++i) { const f32x4 pv = *(const f32x4*)(PL + i * 64 + 4 * k4); acc[i] += pv[0] * w0 + pv[1] * w1 + pv[2] * w2 + pv[3] * w3; }
	v_fmac_f32_e32 v21, v2, v198
	v_fmac_f32_e32 v97, v3, v199
	v_fmac_f32_e32 v21, v4, v200
	v_fmac_f32_e32 v97, v5, v201
	ds_read_b128 v[2:5], v7 offset:3504
	s_waitcnt lgkmcnt(2)
	v_fmac_f32_e32 v21, v24, v202
	v_fmac_f32_e32 v97, v25, v203
	v_fmac_f32_e32 v21, v26, v204
	v_fmac_f32_e32 v97, v27, v205
	ds_read_b128 v[24:27], v7 offset:3520
	s_waitcnt lgkmcnt(2)
	v_fmac_f32_e32 v21, v28, v206
	v_fmac_f32_e32 v97, v29, v207
	v_fmac_f32_e32 v21, v30, v208
	v_fmac_f32_e32 v97, v31, v209
	ds_read_b128 v[28:31], v7 offset:3536
	s_waitcnt lgkmcnt(2)
	v_fmac_f32_e32 v21, v2, v210
	v_fmac_f32_e32 v97, v3, v211
	v_fmac_f32_e32 v21, v4, v212
	v_fmac_f32_e32 v97, v5, v213
	ds_read_b128 v[2:5], v7 offset:3552
	s_waitcnt lgkmcnt(2)
	v_fmac_f32_e32 v21, v24, v214
	v_fmac_f32_e32 v97, v25, v215
	v_fmac_f32_e32 v21, v26, v216
	v_fmac_f32_e32 v97, v27, v217
	ds_read_b128 v[24:27], v7 offset:3568
	s_waitcnt lgkmcnt(2)
	v_fmac_f32_e32 v21, v28, v218
	v_fmac_f32_e32 v97, v29, v219
	v_fmac_f32_e32 v21, v30, v220
	v_fmac_f32_e32 v97, v31, v221
	ds_read_b128 v[28:31], v7 offset:3584
	s_waitcnt lgkmcnt(2)
	v_fmac_f32_e32 v21, v2, v222
	v_fmac_f32_e32 v97, v3, v223
	v_fmac_f32_e32 v21, v4, v224
	v_fmac_f32_e32 v97, v5, v225
	ds_read_b128 v[2:5], v7 offset:3600
	s_waitcnt lgkmcnt(2)
	v_fmac_f32_e32 v21, v24, v226
	v_fmac_f32_e32 v97, v25, v227
	v_fmac_f32_e32 v21, v26, v228
	v_fmac_f32_e32 v97, v27, v229
	v_add_f32_e32 v21, v21, v97
	ds_read_b128 v[24:27], v7 offset:3616
	s_waitcnt lgkmcnt(2)
	v_mul_f32_e32 v22, v28, v146
	v_mul_f32_e32 v96, v29, v147
	v_fmac_f32_e32 v22, v30, v148
	v_fmac_f32_e32 v96, v31, v149
	ds_read_b128 v[28:31], v7 offset:3632
	s_waitcnt lgkmcnt(2)
	v_fmac_f32_e32 v22, v2, v150
	v_fmac_f32_e32 v96, v3, v151
	v_fmac_f32_e32 v22, v4, v152
	v_fmac_f32_e32 v96, v5, v153
	ds_read_b128 v[2:5], v7 offset:3648
	s_waitcnt lgkmcnt(2)
	v_fmac_f32_e32 v22, v24, v154
	v_fmac_f32_e32 v96, v25, v155
	v_fmac_f32_e32 v22, v26, v156
	v_fmac_f32_e32 v96, v27, v157
	ds_read_b128 v[24:27], v7 offset:3664
	s_waitcnt lgkmcnt(2)
	v_fmac_f32_e32 v22, v28, v158
	v_fmac_f32_e32 v96, v29, v159
	v_fmac_f32_e32 v22, v30, v160
	v_fmac_f32_e32 v96, v31, v161
	ds_read_b128 v[28:31], v7 offset:3680
	s_waitcnt lgkmcnt(2)
	v_fmac_f32_e32 v22, v2, v162
	v_fmac_f32_e32 v96, v3, v163
	v_fmac_f32_e32 v22, v4, v164
	v_fmac_f32_e32 v96, v5, v165
	ds_read_b128 v[2:5], v7 offset:3696
	s_waitcnt lgkmcnt(2)
	v_fmac_f32_e32 v22, v24, v184
	v_fmac_f32_e32 v96, v25, v185
	v_fmac_f32_e32 v22, v26, v186
	v_fmac_f32_e32 v96, v27, v187
	ds_read_b128 v[24:27], v7 offset:3712
	s_waitcnt lgkmcnt(2)
	v_fmac_f32_e32 v22, v28, v188
	v_fmac_f32_e32 v96, v29, v189
	v_fmac_f32_e32 v22, v30, v190
	v_fmac_f32_e32 v96, v31, v191
	ds_read_b128 v[28:31], v7 offset:3728
	s_waitcnt lgkmcnt(2)
	v_fmac_f32_e32 v22, v2, v192
	v_fmac_f32_e32 v96, v3, v193
	v_fmac_f32_e32 v22, v4, v196
	v_fmac_f32_e32 v96, v5, v197
	ds_read_b128 v[2:5], v7 offset:3744
	s_waitcnt lgkmcnt(2)
	v_fmac_f32_e32 v22, v24, v198
	v_fmac_f32_e32 v96, v25, v199
	v_fmac_f32_e32 v22, v26, v200
	v_fmac_f32_e32 v96, v27, v201
	ds_read_b128 v[24:27], v7 offset:3760
	s_waitcnt lgkmcnt(2)
	v_fmac_f32_e32 v22, v28, v202
	v_fmac_f32_e32 v96, v29, v203
	v_fmac_f32_e32 v22, v30, v204
	v_fmac_f32_e32 v96, v31, v205
	ds_read_b128 v[28:31], v7 offset:3776
	s_waitcnt lgkmcnt(2)
	v_fmac_f32_e32 v22, v2, v206
	v_fmac_f32_e32 v96, v3, v207
	v_fmac_f32_e32 v22, v4, v208
	v_fmac_f32_e32 v96, v5, v209
	ds_read_b128 v[2:5], v7 offset:3792
	s_waitcnt lgkmcnt(2)
	v_fmac_f32_e32 v22, v24, v210
	v_fmac_f32_e32 v96, v25, v211
	v_fmac_f32_e32 v22, v26, v212
	v_fmac_f32_e32 v96, v27, v213
	ds_read_b128 v[24:27], v7 offset:3808
	s_waitcnt lgkmcnt(2)
	v_fmac_f32_e32 v22, v28, v214
	v_fmac_f32_e32 v96, v29, v215
	v_fmac_f32_e32 v22, v30, v216
	v_fmac_f32_e32 v96, v31, v217
	ds_read_b128 v[28:31], v7 offset:3824
	s_waitcnt lgkmcnt(2)
	v_fmac_f32_e32 v22, v2, v218
	v_fmac_f32_e32 v96, v3, v219
	v_fmac_f32_e32 v22, v4, v220
	v_fmac_f32_e32 v96, v5, v221
	ds_read_b128 v[2:5], v7 offset:3840
	s_waitcnt lgkmcnt(2)
	v_fmac_f32_e32 v22, v24, v222
	v_fmac_f32_e32 v96, v25, v223
	v_fmac_f32_e32 v22, v26, v224
	v_fmac_f32_e32 v96, v27, v225
	ds_read_b128 v[24:27], v7 offset:3856
	s_waitcnt lgkmcnt(2)
	v_fmac_f32_e32 v22, v28, v226
	v_fmac_f32_e32 v96, v29, v227
	v_fmac_f32_e32 v22, v30, v228
	v_fmac_f32_e32 v96, v31, v229
	v_add_f32_e32 v22, v22, v96
	ds_read_b128 v[28:31], v7 offset:3872
	s_waitcnt lgkmcnt(2)
	v_mul_f32_e32 v23, v2, v146
	v_mul_f32_e32 v97, v3, v147
	v_fmac_f32_e32 v23, v4, v148
	v_fmac_f32_e32 v97, v5, v149
	ds_read_b128 v[2:5], v7 offset:3888
	s_waitcnt lgkmcnt(2)
	v_fmac_f32_e32 v23, v24, v150
	v_fmac_f32_e32 v97, v25, v151
	v_fmac_f32_e32 v23, v26, v152
	v_fmac_f32_e32 v97, v27, v153
	ds_read_b128 v[24:27], v7 offset:3904
	s_waitcnt lgkmcnt(2)
	v_fmac_f32_e32 v23, v28, v154
	v_fmac_f32_e32 v97, v29, v155
	v_fmac_f32_e32 v23, v30, v156
	v_fmac_f32_e32 v97, v31, v157
	ds_read_b128 v[28:31], v7 offset:3920
	s_waitcnt lgkmcnt(2)
	v_fmac_f32_e32 v23, v2, v158
	v_fmac_f32_e32 v97, v3, v159
	v_fmac_f32_e32 v23, v4, v160
	v_fmac_f32_e32 v97, v5, v161
	ds_read_b128 v[2:5], v7 offset:3936
	s_waitcnt lgkmcnt(2)
	v_fmac_f32_e32 v23, v24, v162
	v_fmac_f32_e32 v97, v25, v163
	v_fmac_f32_e32 v23, v26, v164
	v_fmac_f32_e32 v97, v27, v165
	ds_read_b128 v[24:27], v7 offset:3952
	s_waitcnt lgkmcnt(2)
	v_fmac_f32_e32 v23, v28, v184
	v_fmac_f32_e32 v97, v29, v185
	v_fmac_f32_e32 v23, v30, v186
	v_fmac_f32_e32 v97, v31, v187
	ds_read_b128 v[28:31], v7 offset:3968
	s_waitcnt lgkmcnt(2)
	v_fmac_f32_e32 v23, v2, v188
	v_fmac_f32_e32 v97, v3, v189
	v_fmac_f32_e32 v23, v4, v190
	v_fmac_f32_e32 v97, v5, v191
	ds_read_b128 v[2:5], v7 offset:3984
	s_waitcnt lgkmcnt(2)
; __device__ __forceinline__ unsigned cvt_pk_bf16(float lo, float hi) { unsigned r; asm volatile("v_cvt_pk_bf16_f32 %0, %1, %2" : "=v"(r) : "v"(lo), "v"(hi)); return r; }
; template <int MODE>
; __device__ __forceinline__ void poolconv_wave(const Ctx& C, int l, int ch, int g, int lane, float* PL) {
;     ...
;     for (int k4 = 0; k4 < 16; ++k4) {
;         const float w0 = wp[(4 * k4 + 0) * 64], w1 = wp[(4 * k4 + 1) * 64], w2 = wp[(4 * k4 + 2) * 64], w3 = wp[(4 * k4 + 3) * 64];
; #pragma unroll
;         for (int i = 0; i < 16; ++i) { const f32x4 pv = *(const f32x4*)(PL + i * 64 + 4 * k4); acc[i] += pv[0] * w0 + pv[1] * w1 + pv[2] * w2 + pv[3] * w3; }
;     }
;     asm volatile("s_waitcnt lgkmcnt(0)" ::: "memory");
;     const float sc = C.in[14][l * 256 + c];
;     const bool st_out = samp || t0 == 4096;
;     float* pout = C.out + (samp ? OFF_PS + ((size_t)l * 32 + b) * 15 * 256 : OFF_PP + ((size_t)l * 4 + b) * 15 * 256) + c;
; #pragma unroll
;     for (int i = 0; i < 16; ++i) {
;         C.PRE[(rowbase + i) * DM + c] = (bf16_t)(cvt_pk_bf16(acc[i] * sc, 0.f) & 0xffffu);
;         if (st_out && i >= 1) pout[(i - 1) * 256] = a[i];
	v_fmac_f32_e32 v23, v24, v192
	v_fmac_f32_e32 v97, v25, v193
	v_fmac_f32_e32 v23, v26, v196
	v_fmac_f32_e32 v97, v27, v197
	ds_read_b128 v[24:27], v7 offset:4000
	s_waitcnt lgkmcnt(2)
	v_fmac_f32_e32 v23, v28, v198
	v_fmac_f32_e32 v97, v29, v199
	v_fmac_f32_e32 v23, v30, v200
	v_fmac_f32_e32 v97, v31, v201
	ds_read_b128 v[28:31], v7 offset:4016
	s_waitcnt lgkmcnt(2)
	v_fmac_f32_e32 v23, v2, v202
	v_fmac_f32_e32 v97, v3, v203
	v_fmac_f32_e32 v23, v4, v204
	v_fmac_f32_e32 v97, v5, v205
	ds_read_b128 v[2:5], v7 offset:4032
	s_waitcnt lgkmcnt(2)
	v_fmac_f32_e32 v23, v24, v206
	v_fmac_f32_e32 v97, v25, v207
	v_fmac_f32_e32 v23, v26, v208
	v_fmac_f32_e32 v97, v27, v209
	ds_read_b128 v[24:27], v7 offset:4048
	s_waitcnt lgkmcnt(2)
	v_fmac_f32_e32 v23, v28, v210
	v_fmac_f32_e32 v97, v29, v211
	v_fmac_f32_e32 v23, v30, v212
	v_fmac_f32_e32 v97, v31, v213
	ds_read_b128 v[28:31], v7 offset:4064
	s_waitcnt lgkmcnt(2)
	v_fmac_f32_e32 v23, v2, v214
	v_fmac_f32_e32 v97, v3, v215
	v_fmac_f32_e32 v23, v4, v216
	v_fmac_f32_e32 v97, v5, v217
	ds_read_b128 v[2:5], v7 offset:4080
	s_waitcnt lgkmcnt(2)
	v_fmac_f32_e32 v23, v24, v218
	v_fmac_f32_e32 v97, v25, v219
	v_fmac_f32_e32 v23, v26, v220
	v_fmac_f32_e32 v97, v27, v221
	s_waitcnt lgkmcnt(1)
	v_fmac_f32_e32 v23, v28, v222
	v_fmac_f32_e32 v97, v29, v223
	v_fmac_f32_e32 v23, v30, v224
	v_fmac_f32_e32 v97, v31, v225
	s_waitcnt lgkmcnt(0)
	v_fmac_f32_e32 v23, v2, v226
	v_fmac_f32_e32 v97, v3, v227
	v_fmac_f32_e32 v23, v4, v228
	v_fmac_f32_e32 v97, v5, v229
	v_add_f32_e32 v23, v23, v97
	s_waitcnt lgkmcnt(0)
	global_load_dword v73, v[42:43], off
	v_lshl_add_u64 v[94:95], s[0:1], 2, v[32:33]
	s_or_b32 s0, s18, 1
	s_mov_b32 s1, s19
	s_mov_b32 s39, 0xc6a4000
	s_mov_b32 s38, 0xc6a2000
	s_lshl_b64 s[26:27], s[0:1], 11
	v_add_co_u32_e64 v98, s[0:1], s39, v94
	s_mov_b32 s40, 0xc6a3000
	v_add_co_u32_e32 v96, vcc, s38, v94
	v_addc_co_u32_e64 v99, s[0:1], 0, v95, s[0:1]
	v_lshl_add_u64 v[2:3], v[34:35], 0, s[14:15]
	s_mov_b64 s[0:1], vcc
	v_add_co_u32_e32 v100, vcc, s40, v94
	s_or_b32 s14, s18, 2
	s_mov_b32 s15, s19
	v_addc_co_u32_e32 v101, vcc, 0, v95, vcc
	s_or_b32 s16, s18, 3
	s_mov_b32 s17, s19
	s_lshl_b64 s[52:53], s[14:15], 11
	v_lshl_add_u64 v[90:91], v[34:35], 0, s[26:27]
	v_addc_co_u32_e64 v97, s[0:1], 0, v95, s[0:1]
	s_or_b32 s20, s18, 4
	s_mov_b32 s21, s19
	s_lshl_b64 s[50:51], s[16:17], 11
	v_lshl_add_u64 v[92:93], v[34:35], 0, s[52:53]
	s_or_b32 s22, s18, 5
	s_mov_b32 s23, s19
	s_lshl_b64 s[48:49], s[20:21], 11
	v_lshl_add_u64 v[88:89], v[34:35], 0, s[50:51]
	s_or_b32 s24, s18, 6
	s_mov_b32 s25, s19
	s_lshl_b64 s[14:15], s[22:23], 11
	v_lshl_add_u64 v[86:87], v[34:35], 0, s[48:49]
	s_or_b32 s28, s18, 7
	s_mov_b32 s29, s19
	s_lshl_b64 s[16:17], s[24:25], 11
	v_lshl_add_u64 v[30:31], v[34:35], 0, s[14:15]
	s_or_b32 s34, s18, 8
	s_mov_b32 s35, s19
	s_or_b32 s36, s18, 9
	s_mov_b32 s37, s19
	s_lshl_b64 s[20:21], s[28:29], 11
	v_lshl_add_u64 v[28:29], v[34:35], 0, s[16:17]
	s_lshl_b64 s[22:23], s[34:35], 11
	s_lshl_b64 s[24:25], s[36:37], 11
	v_lshl_add_u64 v[26:27], v[34:35], 0, s[20:21]
	s_mov_b32 s0, 0xc6a5000
	v_lshl_add_u64 v[24:25], v[34:35], 0, s[22:23]
	v_lshl_add_u64 v[4:5], v[34:35], 0, s[24:25]
	s_mov_b32 s1, s19
	s_waitcnt vmcnt(0)
	v_mul_f32_e32 v7, v8, v73
	v_cvt_pk_bf16_f32 v7, v7, v1
	v_mul_f32_e32 v8, v9, v73
	global_store_short v[2:3], v7, off
	v_cvt_pk_bf16_f32 v7, v8, v1
	v_mul_f32_e32 v9, v10, v73
	global_store_dword v[100:101], v84, off offset:-4096
	global_store_short v[90:91], v7, off
	v_cvt_pk_bf16_f32 v7, v9, v1
	v_mul_f32_e32 v10, v11, v73
	global_store_dword v[96:97], v80, off offset:1024
	global_store_short v[92:93], v7, off
	v_cvt_pk_bf16_f32 v7, v10, v1
	v_mul_f32_e32 v11, v12, v73
	global_store_dword v[96:97], v85, off offset:2048
	global_store_short v[88:89], v7, off
	v_cvt_pk_bf16_f32 v7, v11, v1
	v_mul_f32_e32 v12, v13, v73
	global_store_dword v[96:97], v78, off offset:3072
	global_store_short v[86:87], v7, off
	v_cvt_pk_bf16_f32 v7, v12, v1
	v_mul_f32_e32 v13, v14, v73
	global_store_dword v[100:101], v82, off
	global_store_short v[30:31], v7, off
	v_cvt_pk_bf16_f32 v7, v13, v1
	v_mul_f32_e32 v14, v15, v73
	global_store_dword v[100:101], v76, off offset:1024
	global_store_short v[28:29], v7, off
	v_cvt_pk_bf16_f32 v7, v14, v1
	v_mul_f32_e32 v15, v16, v73
	v_mul_f32_e32 v16, v17, v73
	global_store_dword v[100:101], v83, off offset:2048
	global_store_short v[26:27], v7, off
	v_cvt_pk_bf16_f32 v7, v15, v1
	global_store_dword v[100:101], v74, off offset:3072
	global_store_short v[24:25], v7, off
	v_cvt_pk_bf16_f32 v7, v16, v1
	v_add_co_u32_e32 v16, vcc, s0, v94
	s_or_b32 s0, s18, 10
	global_store_short v[4:5], v7, off
	v_addc_co_u32_e32 v17, vcc, 0, v95, vcc
	v_mul_f32_e32 v7, v18, v73
	s_lshl_b64 s[38:39], s[0:1], 11
	global_store_dword v[16:17], v70, off offset:-4096
	v_cvt_pk_bf16_f32 v7, v7, v1
	v_lshl_add_u64 v[8:9], v[34:35], 0, s[38:39]
	s_or_b32 s0, s18, 11
	global_store_short v[8:9], v7, off
	global_store_dword v[98:99], v72, off offset:1024
	v_mul_f32_e32 v7, v19, v73
	s_lshl_b64 s[40:41], s[0:1], 11
	v_cvt_pk_bf16_f32 v7, v7, v1
	v_lshl_add_u64 v[10:11], v[34:35], 0, s[40:41]
	s_or_b32 s0, s18, 12
	global_store_short v[10:11], v7, off
	global_store_dword v[98:99], v71, off offset:2048
	v_mul_f32_e32 v7, v20, v73
	s_lshl_b64 s[42:43], s[0:1], 11
	v_cvt_pk_bf16_f32 v7, v7, v1
	v_lshl_add_u64 v[12:13], v[34:35], 0, s[42:43]
	s_or_b32 s0, s18, 13
	global_store_short v[12:13], v7, off
	global_store_dword v[98:99], v0, off offset:3072
	v_mul_f32_e32 v0, v21, v73
	s_lshl_b64 s[44:45], s[0:1], 11
	v_cvt_pk_bf16_f32 v0, v0, v1
	v_lshl_add_u64 v[14:15], v[34:35], 0, s[44:45]
; __device__ __forceinline__ unsigned cvt_pk_bf16(float lo, float hi) { unsigned r; asm volatile("v_cvt_pk_bf16_f32 %0, %1, %2" : "=v"(r) : "v"(lo), "v"(hi)); return r; }
; __device__ __forceinline__ float bf2f(unsigned short b) { return __uint_as_float(((unsigned)b) << 16); }
; template <int MODE>
; __device__ __forceinline__ void poolconv_wave(const Ctx& C, int l, int ch, int g, int lane, float* PL) {
;     ...
;     for (int i = 0; i < 16; ++i) {
;         C.PRE[(rowbase + i) * DM + c] = (bf16_t)(cvt_pk_bf16(acc[i] * sc, 0.f) & 0xffffu);
;         if (st_out && i >= 1) pout[(i - 1) * 256] = a[i];
;     }
;     const float cw0 = C.in[16][(l * 3 + 0) * 256 + c], cw1 = C.in[16][(l * 3 + 1) * 256 + c], cw2 = C.in[16][(l * 3 + 2) * 256 + c];
;     float e[18], gb[16];
; #pragma unroll
;     for (int i = 0; i < 18; ++i) {
;         float v;
;         if (MODE == 0 || i >= 2) { const bf16_t* r = C.PAB + (rowbase + (i - 2)) * DM; v = bf2f(r[768 + c]) * bf2f(r[256 + c]); }
;         else if (MODE == 2) v = sconv[i * 256 + c];
;         else v = 0.f;
;         e[i] = v;
;     }
; #pragma unroll
;     for (int i = 0; i < 16; ++i) gb[i] = bf2f(C.PAB[(rowbase + i) * DM + 512 + c]);
	s_or_b32 s0, s18, 14
	global_store_short v[14:15], v0, off
	global_store_dword v[16:17], v6, off
	v_mul_f32_e32 v0, v22, v73
	s_lshl_b64 s[46:47], s[0:1], 11
	v_cvt_pk_bf16_f32 v0, v0, v1
	v_lshl_add_u64 v[6:7], v[34:35], 0, s[46:47]
	global_store_short v[6:7], v0, off
	global_store_dword v[16:17], v68, off offset:1024
	v_mul_f32_e32 v0, v23, v73
	v_cvt_pk_bf16_f32 v0, v0, v1
	global_load_ushort v68, v[52:53], off offset:1536
	global_load_ushort v70, v[52:53], off offset:512
	global_load_ushort v71, v[52:53], off offset:3584
	global_load_ushort v72, v[52:53], off offset:2560
	global_load_ushort v73, v[66:67], off offset:1536
	global_load_ushort v74, v[66:67], off offset:3584
	global_load_ushort v75, v[62:63], off offset:1536
	global_load_ushort v76, v[62:63], off offset:3584
	global_load_ushort v77, v[62:63], off offset:2560
	s_nop 0
	global_load_ushort v62, v[62:63], off offset:512
	s_nop 0
	global_load_ushort v63, v[66:67], off offset:2560
	s_nop 0
	global_load_ushort v66, v[66:67], off offset:512
	s_or_b32 s18, s18, 15
	global_store_dword v[16:17], v69, off offset:2048
	global_load_ushort v67, v[64:65], off offset:1536
	s_nop 0
	global_load_ushort v69, v[64:65], off offset:3584
	global_load_ushort v78, v[58:59], off offset:1536
	global_load_ushort v79, v[58:59], off offset:3584
	global_load_ushort v80, v[58:59], off offset:2560
	global_load_ushort v81, v[58:59], off offset:512
	global_load_ushort v82, v[64:65], off offset:2560
	s_nop 0
	global_load_ushort v64, v[64:65], off offset:512
	s_nop 0
	global_load_ushort v65, v[60:61], off offset:1536
	global_load_ushort v83, v[60:61], off offset:3584
	global_load_ushort v84, v[56:57], off offset:1536
	global_load_ushort v85, v[56:57], off offset:3584
	global_load_ushort v94, v[56:57], off offset:2560
	global_load_ushort v95, v[56:57], off offset:512
	global_load_ushort v96, v[60:61], off offset:2560
	global_load_ushort v97, v[60:61], off offset:512
	v_lshl_add_u64 v[18:19], v[40:41], 0, s[52:53]
	v_lshl_add_u64 v[20:21], v[40:41], 0, s[50:51]
	v_lshl_add_u64 v[22:23], v[40:41], 0, s[48:49]
	v_lshl_add_u64 v[56:57], v[40:41], 0, s[26:27]
	s_lshl_b64 s[34:35], s[18:19], 11
	global_load_ushort v98, v[54:55], off offset:1536
	global_load_ushort v99, v[54:55], off offset:3584
	global_load_ushort v100, v[18:19], off offset:1024
	global_load_ushort v101, v[20:21], off offset:1024
	global_load_ushort v102, v[22:23], off offset:1024
	global_load_ushort v103, v[56:57], off offset:1024
	global_load_ushort v104, v[54:55], off offset:2560
	global_load_ushort v105, v[54:55], off offset:512
	global_load_ushort v106, v[52:53], off offset:1024
	v_lshl_add_u64 v[18:19], v[40:41], 0, s[14:15]
	v_lshl_add_u64 v[20:21], v[40:41], 0, s[16:17]
	v_lshl_add_u64 v[22:23], v[40:41], 0, s[20:21]
	v_lshl_add_u64 v[52:53], v[40:41], 0, s[22:23]
	v_lshl_add_u64 v[54:55], v[40:41], 0, s[24:25]
	v_lshl_add_u64 v[56:57], v[40:41], 0, s[38:39]
	s_lshl_b64 s[0:1], s[2:3], 11
	v_lshl_add_u64 v[58:59], v[40:41], 0, s[40:41]
	v_lshl_add_u64 v[60:61], v[40:41], 0, s[42:43]
	global_load_ushort v107, v[18:19], off offset:1024
	global_load_ushort v108, v[20:21], off offset:1024
	global_load_ushort v109, v[22:23], off offset:1024
	s_nop 0
	global_load_ushort v52, v[52:53], off offset:1024
	s_nop 0
	global_load_ushort v53, v[54:55], off offset:1024
	s_nop 0
	global_load_ushort v54, v[56:57], off offset:1024
	global_load_ushort v55, v[58:59], off offset:1024
	s_nop 0
	global_load_ushort v56, v[60:61], off offset:1024
	v_lshl_add_u64 v[18:19], v[40:41], 0, s[44:45]
	v_lshl_add_u64 v[20:21], v[40:41], 0, s[46:47]
	v_lshl_add_u64 v[22:23], v[40:41], 0, s[34:35]
	v_lshl_add_u64 v[16:17], v[38:39], 0, s[0:1]
	global_load_ushort v18, v[18:19], off offset:1024
	s_nop 0
	global_load_ushort v19, v[20:21], off offset:1024
	s_nop 0
	global_load_ushort v20, v[22:23], off offset:1024
	global_load_dword v21, v[16:17], off
	s_nop 0
	global_load_dword v22, v[16:17], off offset:1024
	global_load_dword v23, v[46:47], off
	global_load_dword v57, v[48:49], off
	global_load_dword v58, v[44:45], off
	v_lshl_add_u64 v[16:17], v[34:35], 0, s[34:35]
	global_store_short v[16:17], v0, off
	s_waitcnt vmcnt(54)
	v_lshlrev_b32_e32 v0, 16, v68
	s_waitcnt vmcnt(53)
	v_lshlrev_b32_e32 v59, 16, v70
	v_mul_f32_e32 v0, v0, v59
	s_waitcnt vmcnt(52)
	v_lshlrev_b32_e32 v59, 16, v71
	s_waitcnt vmcnt(51)
	v_lshlrev_b32_e32 v60, 16, v72
	v_mul_f32_e32 v59, v59, v60
	s_waitcnt vmcnt(50)
	v_lshlrev_b32_e32 v60, 16, v73
	s_waitcnt vmcnt(34)
	v_lshlrev_b32_e32 v64, 16, v64
	v_lshlrev_b32_e32 v68, 16, v81
	v_lshlrev_b32_e32 v62, 16, v62
	v_lshlrev_b32_e32 v63, 16, v63
	v_lshlrev_b32_e32 v61, 16, v66
	v_mul_f32_e32 v60, v60, v61
	v_lshlrev_b32_e32 v61, 16, v74
	v_mul_f32_e32 v61, v61, v63
	v_lshlrev_b32_e32 v63, 16, v75
	v_mul_f32_e32 v62, v63, v62
	v_lshlrev_b32_e32 v63, 16, v76
	v_lshlrev_b32_e32 v66, 16, v77
	v_mul_f32_e32 v63, v63, v66
	v_lshlrev_b32_e32 v66, 16, v67
	v_mul_f32_e32 v64, v66, v64
	v_lshlrev_b32_e32 v66, 16, v69
	v_lshlrev_b32_e32 v67, 16, v82
	v_mul_f32_e32 v66, v66, v67
	v_lshlrev_b32_e32 v67, 16, v78
	v_mul_f32_e32 v67, v67, v68
	v_lshlrev_b32_e32 v68, 16, v79
	v_lshlrev_b32_e32 v69, 16, v80
	v_mul_f32_e32 v68, v68, v69
	s_waitcnt vmcnt(33)
; __device__ __forceinline__ unsigned cvt_pk_bf16(float lo, float hi) { unsigned r; asm volatile("v_cvt_pk_bf16_f32 %0, %1, %2" : "=v"(r) : "v"(lo), "v"(hi)); return r; }
; template <int MODE>
; __device__ __forceinline__ void poolconv_wave(const Ctx& C, int l, int ch, int g, int lane, float* PL) {
;     ...
;     float* cout = C.out + (samp ? OFF_CS + ((size_t)l * 32 + b) * 2 * 256 : OFF_CP + ((size_t)l * 4 + b) * 2 * 256) + c;
; #pragma unroll
;     for (int i = 0; i < 16; ++i) {
;         const float y = gb[i] * (cw0 * e[i] + cw1 * e[i + 1] + cw2 * e[i + 2]);
;         C.PRE[(rowbase + i) * DM + 256 + c] = (bf16_t)(cvt_pk_bf16(y, 0.f) & 0xffffu);
;         if (st_out && i >= 14) cout[(i - 14) * 256] = e[i + 2];
;     }
	v_lshlrev_b32_e32 v65, 16, v65
	s_waitcnt vmcnt(26)
	v_lshlrev_b32_e32 v69, 16, v97
	v_mul_f32_e32 v65, v65, v69
	v_lshlrev_b32_e32 v69, 16, v83
	v_lshlrev_b32_e32 v70, 16, v96
	v_mul_f32_e32 v69, v69, v70
	v_lshlrev_b32_e32 v70, 16, v84
	v_lshlrev_b32_e32 v71, 16, v95
	v_mul_f32_e32 v70, v70, v71
	v_lshlrev_b32_e32 v71, 16, v85
	v_lshlrev_b32_e32 v72, 16, v94
	v_mul_f32_e32 v71, v71, v72
	s_waitcnt vmcnt(25)
	v_lshlrev_b32_e32 v72, 16, v98
	s_waitcnt vmcnt(18)
	v_lshlrev_b32_e32 v73, 16, v105
	s_waitcnt vmcnt(3)
	v_mul_f32_e32 v83, v23, v22
	v_mul_f32_e32 v72, v72, v73
	v_lshlrev_b32_e32 v73, 16, v99
	v_lshlrev_b32_e32 v74, 16, v104
	s_waitcnt vmcnt(1)
	v_fmac_f32_e32 v83, v58, v21
	v_mul_f32_e32 v73, v73, v74
	v_lshlrev_b32_e32 v74, 16, v106
	v_fmac_f32_e32 v83, v57, v0
	v_mul_f32_e32 v21, v83, v74
	v_cvt_pk_bf16_f32 v21, v21, v1
	global_store_short v[2:3], v21, off offset:512
	v_mul_f32_e32 v3, v23, v0
	v_fmac_f32_e32 v3, v58, v22
	v_lshlrev_b32_e32 v2, 16, v103
	v_fmac_f32_e32 v3, v57, v59
	v_mul_f32_e32 v2, v3, v2
	v_cvt_pk_bf16_f32 v2, v2, v1
	global_store_short v[90:91], v2, off offset:512
	v_mul_f32_e32 v2, v23, v59
	v_fmac_f32_e32 v2, v58, v0
	v_lshlrev_b32_e32 v75, 16, v100
	v_fmac_f32_e32 v2, v57, v60
	v_mul_f32_e32 v0, v2, v75
	v_cvt_pk_bf16_f32 v0, v0, v1
	global_store_short v[92:93], v0, off offset:512
	v_mul_f32_e32 v0, v23, v60
	v_fmac_f32_e32 v0, v58, v59
	v_lshlrev_b32_e32 v76, 16, v101
	v_fmac_f32_e32 v0, v57, v61
	v_mul_f32_e32 v0, v0, v76
	v_cvt_pk_bf16_f32 v0, v0, v1
	global_store_short v[88:89], v0, off offset:512
	v_mul_f32_e32 v0, v23, v61
	v_fmac_f32_e32 v0, v58, v60
	v_lshlrev_b32_e32 v77, 16, v102
	v_fmac_f32_e32 v0, v57, v62
	v_mul_f32_e32 v0, v0, v77
	v_cvt_pk_bf16_f32 v0, v0, v1
	global_store_short v[86:87], v0, off offset:512
	v_mul_f32_e32 v0, v23, v62
	v_fmac_f32_e32 v0, v58, v61
	v_lshlrev_b32_e32 v78, 16, v107
	v_fmac_f32_e32 v0, v57, v63
	v_mul_f32_e32 v0, v0, v78
	v_cvt_pk_bf16_f32 v0, v0, v1
	global_store_short v[30:31], v0, off offset:512
	v_mul_f32_e32 v0, v23, v63
	v_fmac_f32_e32 v0, v58, v62
	v_lshlrev_b32_e32 v79, 16, v108
	v_fmac_f32_e32 v0, v57, v64
	v_mul_f32_e32 v0, v0, v79
	v_cvt_pk_bf16_f32 v0, v0, v1
	global_store_short v[28:29], v0, off offset:512
	v_mul_f32_e32 v0, v23, v64
	v_fmac_f32_e32 v0, v58, v63
	v_lshlrev_b32_e32 v80, 16, v109
	v_fmac_f32_e32 v0, v57, v66
	v_mul_f32_e32 v0, v0, v80
	v_cvt_pk_bf16_f32 v0, v0, v1
	global_store_short v[26:27], v0, off offset:512
	v_mul_f32_e32 v0, v23, v66
	v_fmac_f32_e32 v0, v58, v64
	v_lshlrev_b32_e32 v52, 16, v52
	v_fmac_f32_e32 v0, v57, v67
	v_mul_f32_e32 v0, v0, v52
	v_cvt_pk_bf16_f32 v0, v0, v1
	global_store_short v[24:25], v0, off offset:512
	v_mul_f32_e32 v0, v23, v67
	v_fmac_f32_e32 v0, v58, v66
	v_lshlrev_b32_e32 v53, 16, v53
	v_fmac_f32_e32 v0, v57, v68
	v_mul_f32_e32 v0, v0, v53
	v_cvt_pk_bf16_f32 v0, v0, v1
	global_store_short v[4:5], v0, off offset:512
	v_mul_f32_e32 v0, v23, v68
	v_fmac_f32_e32 v0, v58, v67
	v_lshlrev_b32_e32 v54, 16, v54
	v_fmac_f32_e32 v0, v57, v65
	v_mul_f32_e32 v0, v0, v54
	v_cvt_pk_bf16_f32 v0, v0, v1
	global_store_short v[8:9], v0, off offset:512
	v_mul_f32_e32 v0, v23, v65
	v_fmac_f32_e32 v0, v58, v68
	v_lshlrev_b32_e32 v55, 16, v55
	v_fmac_f32_e32 v0, v57, v69
	v_mul_f32_e32 v0, v0, v55
	v_cvt_pk_bf16_f32 v0, v0, v1
	global_store_short v[10:11], v0, off offset:512
	v_mul_f32_e32 v0, v23, v69
	v_fmac_f32_e32 v0, v58, v65
	v_lshlrev_b32_e32 v56, 16, v56
	v_fmac_f32_e32 v0, v57, v70
	v_mul_f32_e32 v0, v0, v56
	v_cvt_pk_bf16_f32 v0, v0, v1
	global_store_short v[12:13], v0, off offset:512
	v_mul_f32_e32 v0, v23, v70
	v_fmac_f32_e32 v0, v58, v69
	v_lshlrev_b32_e32 v81, 16, v18
	v_fmac_f32_e32 v0, v57, v71
	v_mul_f32_e32 v0, v0, v81
	v_cvt_pk_bf16_f32 v0, v0, v1
	global_store_short v[14:15], v0, off offset:512
	v_mul_f32_e32 v0, v23, v71
	v_fmac_f32_e32 v0, v58, v70
	v_lshlrev_b32_e32 v82, 16, v19
	v_fmac_f32_e32 v0, v57, v72
	v_mul_f32_e32 v0, v0, v82
	v_cvt_pk_bf16_f32 v0, v0, v1
	global_store_short v[6:7], v0, off offset:512
	v_mul_f32_e32 v0, v23, v72
	v_lshl_add_u64 v[18:19], v[32:33], 0, s[0:1]
	v_fmac_f32_e32 v0, v58, v71
	v_lshlrev_b32_e32 v20, 16, v20
	v_add_co_u32_e32 v2, vcc, 0xc792000, v18
	v_fmac_f32_e32 v0, v57, v73
	s_nop 0
	v_addc_co_u32_e32 v3, vcc, 0, v19, vcc
	v_mul_f32_e32 v0, v0, v20
	global_store_dword v[2:3], v72, off
	v_cvt_pk_bf16_f32 v0, v0, v1
	global_store_short v[16:17], v0, off offset:512
	global_store_dword v[2:3], v73, off offset:1024
	s_branch .LBB0_621
